# phase 2: shift-table items run on waves 0/1 before the row pre-norm, rows handed out to the 8 waves through an LDS counter so the other waves start streaming immediately; DFT items use the same fast p
# speedup vs baseline: 1.0087x; 1.0007x over previous
; __device__ __forceinline__ void prenorm_rows(const float* src0, const float* src1, int row_lo, int row_hi, const float* g, const float* scale, float* SS, bf16_t* HB) {
;     const int lane = threadIdx.x & 63, wave = threadIdx.x >> 6, gw = blockIdx.x * 8 + wave, NGW = gridDim.x * 8;
;     for (int row = row_lo + gw; row < row_hi; row += 2 * NGW) {
; __device__ __forceinline__ void cb_tables(const Params& p) {
;     const int lane = threadIdx.x & 63, wave = threadIdx.x >> 6, G = gridDim.x;
;     unsigned char* ws = p.ws; const float* MOD = (const float*)(ws + WS_MOD);
;     for (int it = blockIdx.x + G * wave; it < 4 * 88 + 40 + 32; it += 8 * G) {
;         if (it < 352) { const int mi = it / 88, ch = it % 88, layer = mi >> 1, sub = mi & 1;
;             cb_item((const bf16_t*)(ws + WS_W1T + mi * SZ_W1T), D, D, ch * 64, MOD + (size_t)layer * 5 * 9216 + (sub ? 6 : 0) * 1024, (float*)(ws + WS_CB) + (size_t)mi * 5 * NFF1, NFF1, lane); }
;         else if (it < 392) { const int ch = it - 352; cb_item((const bf16_t*)(ws + WS_WABT), D, D, ch * 64, MOD + 3 * 1024, (float*)(ws + WS_CBAB), NAB, lane); }
;         else { const int e = it - 392, gr = e >> 3, ch = e & 7;
;             cb_item((const bf16_t*)(ws + WS_DFTC), 256, 256, ch * 64, MOD + (size_t)5 * 9216 + 3 * 1024 + gr * 256, (float*)(ws + WS_CBD) + gr * 512, 2048, lane); }
.LBB0_134:
	s_or_b64 exec, exec, s[0:1]
	s_add_u32 s72, s80, 0xb140000
	s_movk_i32 s19, 0x4400
	s_addc_u32 s73, s81, 0
	v_cmp_gt_i32_e32 vcc, s19, v181
	v_lshlrev_b32_e32 v192, 4, v178
	v_lshlrev_b32_e32 v194, 3, v178
	v_mov_b32_e32 v254, 0x23f10
	v_mov_b32_e32 v255, 0
	ds_write_b32 v254, v255
	s_waitcnt lgkmcnt(0)
	s_barrier
	s_and_saveexec_b64 s[22:23], vcc
	s_cbranch_execz .LBB0_148
	s_cmpk_lg_u32 s82, 0x100
	s_cbranch_scc1 .Lph2_cbdone
	v_readfirstlane_b32 s44, v176
	s_lshr_b32 s44, s44, 6
	s_cmp_gt_u32 s44, 1
	s_cbranch_scc1 .Lph2_cbdone
	s_mov_b64 s[100:101], exec
	s_mov_b64 exec, -1
	s_cmp_eq_u32 s44, 1
	s_cbranch_scc1 .Lph2_w1
	s_cmpk_ge_u32 s84, 0x58
	s_cselect_b32 s42, 1, 0
	s_cmpk_ge_u32 s84, 0xb0
	s_cselect_b32 s43, 1, 0
	s_add_i32 s42, s42, s43
	s_mul_i32 s43, s42, 0x58
	s_sub_i32 s43, s84, s43
	s_mul_i32 s45, s42, 0xb00000
	s_lshl_b32 s0, s43, 17
	s_add_u32 s45, s45, s0
	s_add_u32 s45, s45, 0x200000
	s_add_u32 s34, s80, s45
	s_addc_u32 s35, s81, 0
	s_mov_b32 s45, 0
	s_cmp_eq_u32 s42, 1
	s_cselect_b32 s45, 0x6000, s45
	s_cmp_eq_u32 s42, 2
	s_cselect_b32 s45, 0x2d000, s45
	s_add_u32 s36, s80, s45
	s_addc_u32 s37, s81, 0
	s_mul_i32 s45, s42, 0x1b800
	s_lshl_b32 s0, s43, 8
	s_add_u32 s45, s45, s0
	s_add_u32 s45, s45, 0x100000
	s_add_u32 s38, s80, s45
	s_addc_u32 s39, s81, 0
	s_movk_i32 s40, 0x5800
	s_branch .Lph2_full
.Lph2_w1:
	s_cmpk_lt_u32 s84, 8
	s_cbranch_scc0 .Lph2_w1_ab
	s_mov_b32 s42, 2
	s_add_i32 s43, s84, 0x50
	s_mul_i32 s45, s42, 0xb00000
	s_lshl_b32 s0, s43, 17
	s_add_u32 s45, s45, s0
	s_add_u32 s45, s45, 0x200000
	s_add_u32 s34, s80, s45
	s_addc_u32 s35, s81, 0
	s_mov_b32 s45, 0
	s_cmp_eq_u32 s42, 1
	s_cselect_b32 s45, 0x6000, s45
	s_cmp_eq_u32 s42, 2
	s_cselect_b32 s45, 0x2d000, s45
	s_add_u32 s36, s80, s45
	s_addc_u32 s37, s81, 0
	s_mul_i32 s45, s42, 0x1b800
	s_lshl_b32 s0, s43, 8
	s_add_u32 s45, s45, s0
	s_add_u32 s45, s45, 0x100000
	s_add_u32 s38, s80, s45
	s_addc_u32 s39, s81, 0
	s_movk_i32 s40, 0x5800
	s_branch .Lph2_full
.Lph2_w1_ab:
	s_cmpk_lt_u32 s84, 0x60
	s_cbranch_scc1 .Lph2_cbfin
	s_cmpk_ge_u32 s84, 0x88
	s_cbranch_scc1 .Lph2_w1_dft
	s_sub_i32 s43, s84, 0x60
	s_lshl_b32 s45, s43, 17
	s_add_u32 s45, s45, 0x4400000
	s_add_u32 s34, s80, s45
	s_addc_u32 s35, s81, 0
	s_add_u32 s36, s80, 0x3000
	s_addc_u32 s37, s81, 0
	s_lshl_b32 s45, s43, 8
	s_add_u32 s45, s45, 0x16e000
	s_add_u32 s38, s80, s45
	s_addc_u32 s39, s81, 0
	s_movk_i32 s40, 0x2800
.Lph2_full:
	v_and_b32_e32 v16, 63, v176
	v_lshlrev_b32_e32 v17, 11, v16
	s_lshl_b32 s45, s44, 14
	v_mov_b32_e32 v27, s45
	v_mul_u32_u24_e32 v18, 0xa0, v16
	v_add_u32_e32 v18, s45, v18
	v_lshlrev_b32_e32 v19, 5, v16
	v_mov_b32_e32 v156, 0
	v_mov_b32_e32 v157, 0
	v_mov_b32_e32 v158, 0
	v_mov_b32_e32 v159, 0
	v_mov_b32_e32 v160, 0
	v_mov_b32_e32 v161, 0
	v_mov_b32_e32 v162, 0
	v_mov_b32_e32 v163, 0
	v_mov_b32_e32 v164, 0
	v_mov_b32_e32 v165, 0
	s_add_u32 s0, s36, 0x0
	s_addc_u32 s1, s37, 0
	global_load_dwordx4 v[28:31], v19, s[0:1]
	global_load_dwordx4 v[32:35], v19, s[0:1] offset:16
	s_add_u32 s0, s0, 0x9000
	s_addc_u32 s1, s1, 0
	global_load_dwordx4 v[36:39], v19, s[0:1]
	global_load_dwordx4 v[40:43], v19, s[0:1] offset:16
	s_add_u32 s0, s0, 0x9000
	s_addc_u32 s1, s1, 0
	global_load_dwordx4 v[44:47], v19, s[0:1]
	global_load_dwordx4 v[48:51], v19, s[0:1] offset:16
	s_add_u32 s0, s0, 0x9000
	s_addc_u32 s1, s1, 0
	global_load_dwordx4 v[52:55], v19, s[0:1]
	global_load_dwordx4 v[56:59], v19, s[0:1] offset:16
	s_add_u32 s0, s0, 0x9000
	s_addc_u32 s1, s1, 0
	global_load_dwordx4 v[140:143], v19, s[0:1]
	global_load_dwordx4 v[144:147], v19, s[0:1] offset:16
	s_waitcnt vmcnt(0)
	ds_write_b128 v18, v[28:31]
	ds_write_b128 v18, v[32:35] offset:16
	ds_write_b128 v18, v[36:39] offset:32
	ds_write_b128 v18, v[40:43] offset:48
	ds_write_b128 v18, v[44:47] offset:64
	ds_write_b128 v18, v[48:51] offset:80
	ds_write_b128 v18, v[52:55] offset:96
	ds_write_b128 v18, v[56:59] offset:112
	ds_write_b128 v18, v[140:143] offset:128
	ds_write_b128 v18, v[144:147] offset:144
	s_waitcnt lgkmcnt(0)
	v_add_u32_e32 v25, 0x0, v17
	v_mov_b32_e32 v26, v27
	global_load_dwordx4 v[28:31], v25, s[34:35]
	global_load_dwordx4 v[32:35], v25, s[34:35] offset:16
	global_load_dwordx4 v[36:39], v25, s[34:35] offset:32
	global_load_dwordx4 v[40:43], v25, s[34:35] offset:48
	global_load_dwordx4 v[44:47], v25, s[34:35] offset:64
	global_load_dwordx4 v[48:51], v25, s[34:35] offset:80
	global_load_dwordx4 v[52:55], v25, s[34:35] offset:96
	global_load_dwordx4 v[56:59], v25, s[34:35] offset:112
	ds_read_b128 v[60:63], v26
	ds_read_b128 v[64:67], v26 offset:16
	ds_read_b128 v[68:71], v26 offset:32
	ds_read_b128 v[72:75], v26 offset:48
	ds_read_b128 v[76:79], v26 offset:64
	ds_read_b128 v[80:83], v26 offset:80
	ds_read_b128 v[84:87], v26 offset:96
	ds_read_b128 v[88:91], v26 offset:112
	ds_read_b128 v[92:95], v26 offset:128
	ds_read_b128 v[96:99], v26 offset:144
	s_mov_b32 s41, 8
; __device__ __forceinline__ void cb_item(const bf16_t* WT, int ldw, int K, int n0, const float* shift, float* out, int ostride, int lane) {
;     ...
;     for (int k8 = 0; k8 < K; k8 += 8) {
;         const u32x4 q = *(const u32x4*)(wp + k8);
;         float w[8];
; #pragma unroll
;         for (int e = 0; e < 4; ++e) { w[2 * e] = __uint_as_float(q[e] << 16); w[2 * e + 1] = __uint_as_float(q[e] & 0xffff0000u); }
; #pragma unroll
;         for (int b = 0; b < 5; ++b) { const float* sp = shift + (size_t)b * 9216 + k8;
; #pragma unroll
;             for (int e = 0; e < 8; ++e) a[b] += w[e] * sp[e]; }
;     }
.Lcb1_loop_f_0:
	ds_read_b128 v[100:103], v26 offset:160
	ds_read_b128 v[104:107], v26 offset:176
	ds_read_b128 v[108:111], v26 offset:192
	ds_read_b128 v[112:115], v26 offset:208
	ds_read_b128 v[116:119], v26 offset:224
	ds_read_b128 v[120:123], v26 offset:240
	ds_read_b128 v[124:127], v26 offset:256
	ds_read_b128 v[128:131], v26 offset:272
	ds_read_b128 v[132:135], v26 offset:288
	ds_read_b128 v[136:139], v26 offset:304
	s_waitcnt vmcnt(7)
	v_lshlrev_b32_e32 v148, 16, v28
	v_and_b32_e32 v149, 0xffff0000, v28
	v_lshlrev_b32_e32 v150, 16, v29
	v_and_b32_e32 v151, 0xffff0000, v29
	v_lshlrev_b32_e32 v152, 16, v30
	v_and_b32_e32 v153, 0xffff0000, v30
	v_lshlrev_b32_e32 v154, 16, v31
	v_and_b32_e32 v155, 0xffff0000, v31
	global_load_dwordx4 v[28:31], v25, s[34:35] offset:128
	s_waitcnt lgkmcnt(10)
	v_pk_fma_f32 v[156:157], v[148:149], v[60:61], v[156:157]
	v_pk_fma_f32 v[158:159], v[148:149], v[68:69], v[158:159]
	v_pk_fma_f32 v[160:161], v[148:149], v[76:77], v[160:161]
	v_pk_fma_f32 v[162:163], v[148:149], v[84:85], v[162:163]
	v_pk_fma_f32 v[164:165], v[148:149], v[92:93], v[164:165]
	v_pk_fma_f32 v[156:157], v[150:151], v[62:63], v[156:157]
	v_pk_fma_f32 v[158:159], v[150:151], v[70:71], v[158:159]
	v_pk_fma_f32 v[160:161], v[150:151], v[78:79], v[160:161]
	v_pk_fma_f32 v[162:163], v[150:151], v[86:87], v[162:163]
	v_pk_fma_f32 v[164:165], v[150:151], v[94:95], v[164:165]
	v_pk_fma_f32 v[156:157], v[152:153], v[64:65], v[156:157]
	v_pk_fma_f32 v[158:159], v[152:153], v[72:73], v[158:159]
	v_pk_fma_f32 v[160:161], v[152:153], v[80:81], v[160:161]
	v_pk_fma_f32 v[162:163], v[152:153], v[88:89], v[162:163]
	v_pk_fma_f32 v[164:165], v[152:153], v[96:97], v[164:165]
	v_pk_fma_f32 v[156:157], v[154:155], v[66:67], v[156:157]
	v_pk_fma_f32 v[158:159], v[154:155], v[74:75], v[158:159]
	v_pk_fma_f32 v[160:161], v[154:155], v[82:83], v[160:161]
	v_pk_fma_f32 v[162:163], v[154:155], v[90:91], v[162:163]
	v_pk_fma_f32 v[164:165], v[154:155], v[98:99], v[164:165]
	ds_read_b128 v[60:63], v26 offset:320
	ds_read_b128 v[64:67], v26 offset:336
	ds_read_b128 v[68:71], v26 offset:352
	ds_read_b128 v[72:75], v26 offset:368
	ds_read_b128 v[76:79], v26 offset:384
	ds_read_b128 v[80:83], v26 offset:400
	ds_read_b128 v[84:87], v26 offset:416
	ds_read_b128 v[88:91], v26 offset:432
	ds_read_b128 v[92:95], v26 offset:448
	ds_read_b128 v[96:99], v26 offset:464
	s_waitcnt vmcnt(7)
	v_lshlrev_b32_e32 v148, 16, v32
	v_and_b32_e32 v149, 0xffff0000, v32
	v_lshlrev_b32_e32 v150, 16, v33
	v_and_b32_e32 v151, 0xffff0000, v33
	v_lshlrev_b32_e32 v152, 16, v34
	v_and_b32_e32 v153, 0xffff0000, v34
	v_lshlrev_b32_e32 v154, 16, v35
	v_and_b32_e32 v155, 0xffff0000, v35
	global_load_dwordx4 v[32:35], v25, s[34:35] offset:144
	s_waitcnt lgkmcnt(10)
	v_pk_fma_f32 v[156:157], v[148:149], v[100:101], v[156:157]
	v_pk_fma_f32 v[158:159], v[148:149], v[108:109], v[158:159]
	v_pk_fma_f32 v[160:161], v[148:149], v[116:117], v[160:161]
	v_pk_fma_f32 v[162:163], v[148:149], v[124:125], v[162:163]
	v_pk_fma_f32 v[164:165], v[148:149], v[132:133], v[164:165]
	v_pk_fma_f32 v[156:157], v[150:151], v[102:103], v[156:157]
	v_pk_fma_f32 v[158:159], v[150:151], v[110:111], v[158:159]
	v_pk_fma_f32 v[160:161], v[150:151], v[118:119], v[160:161]
	v_pk_fma_f32 v[162:163], v[150:151], v[126:127], v[162:163]
	v_pk_fma_f32 v[164:165], v[150:151], v[134:135], v[164:165]
	v_pk_fma_f32 v[156:157], v[152:153], v[104:105], v[156:157]
	v_pk_fma_f32 v[158:159], v[152:153], v[112:113], v[158:159]
	v_pk_fma_f32 v[160:161], v[152:153], v[120:121], v[160:161]
	v_pk_fma_f32 v[162:163], v[152:153], v[128:129], v[162:163]
	v_pk_fma_f32 v[164:165], v[152:153], v[136:137], v[164:165]
	v_pk_fma_f32 v[156:157], v[154:155], v[106:107], v[156:157]
	v_pk_fma_f32 v[158:159], v[154:155], v[114:115], v[158:159]
	v_pk_fma_f32 v[160:161], v[154:155], v[122:123], v[160:161]
	v_pk_fma_f32 v[162:163], v[154:155], v[130:131], v[162:163]
	v_pk_fma_f32 v[164:165], v[154:155], v[138:139], v[164:165]
	ds_read_b128 v[100:103], v26 offset:480
	ds_read_b128 v[104:107], v26 offset:496
	ds_read_b128 v[108:111], v26 offset:512
	ds_read_b128 v[112:115], v26 offset:528
	ds_read_b128 v[116:119], v26 offset:544
	ds_read_b128 v[120:123], v26 offset:560
	ds_read_b128 v[124:127], v26 offset:576
	ds_read_b128 v[128:131], v26 offset:592
	ds_read_b128 v[132:135], v26 offset:608
	ds_read_b128 v[136:139], v26 offset:624
	s_waitcnt vmcnt(7)
	v_lshlrev_b32_e32 v148, 16, v36
	v_and_b32_e32 v149, 0xffff0000, v36
	v_lshlrev_b32_e32 v150, 16, v37
	v_and_b32_e32 v151, 0xffff0000, v37
	v_lshlrev_b32_e32 v152, 16, v38
	v_and_b32_e32 v153, 0xffff0000, v38
	v_lshlrev_b32_e32 v154, 16, v39
	v_and_b32_e32 v155, 0xffff0000, v39
	global_load_dwordx4 v[36:39], v25, s[34:35] offset:160
	s_waitcnt lgkmcnt(10)
	v_pk_fma_f32 v[156:157], v[148:149], v[60:61], v[156:157]
	v_pk_fma_f32 v[158:159], v[148:149], v[68:69], v[158:159]
	v_pk_fma_f32 v[160:161], v[148:149], v[76:77], v[160:161]
	v_pk_fma_f32 v[162:163], v[148:149], v[84:85], v[162:163]
	v_pk_fma_f32 v[164:165], v[148:149], v[92:93], v[164:165]
	v_pk_fma_f32 v[156:157], v[150:151], v[62:63], v[156:157]
	v_pk_fma_f32 v[158:159], v[150:151], v[70:71], v[158:159]
	v_pk_fma_f32 v[160:161], v[150:151], v[78:79], v[160:161]
	v_pk_fma_f32 v[162:163], v[150:151], v[86:87], v[162:163]
	v_pk_fma_f32 v[164:165], v[150:151], v[94:95], v[164:165]
	v_pk_fma_f32 v[156:157], v[152:153], v[64:65], v[156:157]
	v_pk_fma_f32 v[158:159], v[152:153], v[72:73], v[158:159]
	v_pk_fma_f32 v[160:161], v[152:153], v[80:81], v[160:161]
	v_pk_fma_f32 v[162:163], v[152:153], v[88:89], v[162:163]
	v_pk_fma_f32 v[164:165], v[152:153], v[96:97], v[164:165]
	v_pk_fma_f32 v[156:157], v[154:155], v[66:67], v[156:157]
	v_pk_fma_f32 v[158:159], v[154:155], v[74:75], v[158:159]
	v_pk_fma_f32 v[160:161], v[154:155], v[82:83], v[160:161]
	v_pk_fma_f32 v[162:163], v[154:155], v[90:91], v[162:163]
	v_pk_fma_f32 v[164:165], v[154:155], v[98:99], v[164:165]
	ds_read_b128 v[60:63], v26 offset:640
	ds_read_b128 v[64:67], v26 offset:656
	ds_read_b128 v[68:71], v26 offset:672
	ds_read_b128 v[72:75], v26 offset:688
	ds_read_b128 v[76:79], v26 offset:704
	ds_read_b128 v[80:83], v26 offset:720
	ds_read_b128 v[84:87], v26 offset:736
	ds_read_b128 v[88:91], v26 offset:752
	ds_read_b128 v[92:95], v26 offset:768
	ds_read_b128 v[96:99], v26 offset:784
	s_waitcnt vmcnt(7)
; __device__ __forceinline__ void cb_item(const bf16_t* WT, int ldw, int K, int n0, const float* shift, float* out, int ostride, int lane) {
;     ...
;     for (int k8 = 0; k8 < K; k8 += 8) {
;         const u32x4 q = *(const u32x4*)(wp + k8);
;         float w[8];
; #pragma unroll
;         for (int e = 0; e < 4; ++e) { w[2 * e] = __uint_as_float(q[e] << 16); w[2 * e + 1] = __uint_as_float(q[e] & 0xffff0000u); }
; #pragma unroll
;         for (int b = 0; b < 5; ++b) { const float* sp = shift + (size_t)b * 9216 + k8;
; #pragma unroll
;             for (int e = 0; e < 8; ++e) a[b] += w[e] * sp[e]; }
;     }
	v_lshlrev_b32_e32 v148, 16, v40
	v_and_b32_e32 v149, 0xffff0000, v40
	v_lshlrev_b32_e32 v150, 16, v41
	v_and_b32_e32 v151, 0xffff0000, v41
	v_lshlrev_b32_e32 v152, 16, v42
	v_and_b32_e32 v153, 0xffff0000, v42
	v_lshlrev_b32_e32 v154, 16, v43
	v_and_b32_e32 v155, 0xffff0000, v43
	global_load_dwordx4 v[40:43], v25, s[34:35] offset:176
	s_waitcnt lgkmcnt(10)
	v_pk_fma_f32 v[156:157], v[148:149], v[100:101], v[156:157]
	v_pk_fma_f32 v[158:159], v[148:149], v[108:109], v[158:159]
	v_pk_fma_f32 v[160:161], v[148:149], v[116:117], v[160:161]
	v_pk_fma_f32 v[162:163], v[148:149], v[124:125], v[162:163]
	v_pk_fma_f32 v[164:165], v[148:149], v[132:133], v[164:165]
	v_pk_fma_f32 v[156:157], v[150:151], v[102:103], v[156:157]
	v_pk_fma_f32 v[158:159], v[150:151], v[110:111], v[158:159]
	v_pk_fma_f32 v[160:161], v[150:151], v[118:119], v[160:161]
	v_pk_fma_f32 v[162:163], v[150:151], v[126:127], v[162:163]
	v_pk_fma_f32 v[164:165], v[150:151], v[134:135], v[164:165]
	v_pk_fma_f32 v[156:157], v[152:153], v[104:105], v[156:157]
	v_pk_fma_f32 v[158:159], v[152:153], v[112:113], v[158:159]
	v_pk_fma_f32 v[160:161], v[152:153], v[120:121], v[160:161]
	v_pk_fma_f32 v[162:163], v[152:153], v[128:129], v[162:163]
	v_pk_fma_f32 v[164:165], v[152:153], v[136:137], v[164:165]
	v_pk_fma_f32 v[156:157], v[154:155], v[106:107], v[156:157]
	v_pk_fma_f32 v[158:159], v[154:155], v[114:115], v[158:159]
	v_pk_fma_f32 v[160:161], v[154:155], v[122:123], v[160:161]
	v_pk_fma_f32 v[162:163], v[154:155], v[130:131], v[162:163]
	v_pk_fma_f32 v[164:165], v[154:155], v[138:139], v[164:165]
	ds_read_b128 v[100:103], v26 offset:800
	ds_read_b128 v[104:107], v26 offset:816
	ds_read_b128 v[108:111], v26 offset:832
	ds_read_b128 v[112:115], v26 offset:848
	ds_read_b128 v[116:119], v26 offset:864
	ds_read_b128 v[120:123], v26 offset:880
	ds_read_b128 v[124:127], v26 offset:896
	ds_read_b128 v[128:131], v26 offset:912
	ds_read_b128 v[132:135], v26 offset:928
	ds_read_b128 v[136:139], v26 offset:944
	s_waitcnt vmcnt(7)
	v_lshlrev_b32_e32 v148, 16, v44
	v_and_b32_e32 v149, 0xffff0000, v44
	v_lshlrev_b32_e32 v150, 16, v45
	v_and_b32_e32 v151, 0xffff0000, v45
	v_lshlrev_b32_e32 v152, 16, v46
	v_and_b32_e32 v153, 0xffff0000, v46
	v_lshlrev_b32_e32 v154, 16, v47
	v_and_b32_e32 v155, 0xffff0000, v47
	global_load_dwordx4 v[44:47], v25, s[34:35] offset:192
	s_waitcnt lgkmcnt(10)
	v_pk_fma_f32 v[156:157], v[148:149], v[60:61], v[156:157]
	v_pk_fma_f32 v[158:159], v[148:149], v[68:69], v[158:159]
	v_pk_fma_f32 v[160:161], v[148:149], v[76:77], v[160:161]
	v_pk_fma_f32 v[162:163], v[148:149], v[84:85], v[162:163]
	v_pk_fma_f32 v[164:165], v[148:149], v[92:93], v[164:165]
	v_pk_fma_f32 v[156:157], v[150:151], v[62:63], v[156:157]
	v_pk_fma_f32 v[158:159], v[150:151], v[70:71], v[158:159]
	v_pk_fma_f32 v[160:161], v[150:151], v[78:79], v[160:161]
	v_pk_fma_f32 v[162:163], v[150:151], v[86:87], v[162:163]
	v_pk_fma_f32 v[164:165], v[150:151], v[94:95], v[164:165]
	v_pk_fma_f32 v[156:157], v[152:153], v[64:65], v[156:157]
	v_pk_fma_f32 v[158:159], v[152:153], v[72:73], v[158:159]
	v_pk_fma_f32 v[160:161], v[152:153], v[80:81], v[160:161]
	v_pk_fma_f32 v[162:163], v[152:153], v[88:89], v[162:163]
	v_pk_fma_f32 v[164:165], v[152:153], v[96:97], v[164:165]
	v_pk_fma_f32 v[156:157], v[154:155], v[66:67], v[156:157]
	v_pk_fma_f32 v[158:159], v[154:155], v[74:75], v[158:159]
	v_pk_fma_f32 v[160:161], v[154:155], v[82:83], v[160:161]
	v_pk_fma_f32 v[162:163], v[154:155], v[90:91], v[162:163]
	v_pk_fma_f32 v[164:165], v[154:155], v[98:99], v[164:165]
	ds_read_b128 v[60:63], v26 offset:960
	ds_read_b128 v[64:67], v26 offset:976
	ds_read_b128 v[68:71], v26 offset:992
	ds_read_b128 v[72:75], v26 offset:1008
	ds_read_b128 v[76:79], v26 offset:1024
	ds_read_b128 v[80:83], v26 offset:1040
	ds_read_b128 v[84:87], v26 offset:1056
	ds_read_b128 v[88:91], v26 offset:1072
	ds_read_b128 v[92:95], v26 offset:1088
	ds_read_b128 v[96:99], v26 offset:1104
	s_waitcnt vmcnt(7)
	v_lshlrev_b32_e32 v148, 16, v48
	v_and_b32_e32 v149, 0xffff0000, v48
	v_lshlrev_b32_e32 v150, 16, v49
	v_and_b32_e32 v151, 0xffff0000, v49
	v_lshlrev_b32_e32 v152, 16, v50
	v_and_b32_e32 v153, 0xffff0000, v50
	v_lshlrev_b32_e32 v154, 16, v51
	v_and_b32_e32 v155, 0xffff0000, v51
	global_load_dwordx4 v[48:51], v25, s[34:35] offset:208
	s_waitcnt lgkmcnt(10)
	v_pk_fma_f32 v[156:157], v[148:149], v[100:101], v[156:157]
	v_pk_fma_f32 v[158:159], v[148:149], v[108:109], v[158:159]
	v_pk_fma_f32 v[160:161], v[148:149], v[116:117], v[160:161]
	v_pk_fma_f32 v[162:163], v[148:149], v[124:125], v[162:163]
	v_pk_fma_f32 v[164:165], v[148:149], v[132:133], v[164:165]
	v_pk_fma_f32 v[156:157], v[150:151], v[102:103], v[156:157]
	v_pk_fma_f32 v[158:159], v[150:151], v[110:111], v[158:159]
	v_pk_fma_f32 v[160:161], v[150:151], v[118:119], v[160:161]
	v_pk_fma_f32 v[162:163], v[150:151], v[126:127], v[162:163]
	v_pk_fma_f32 v[164:165], v[150:151], v[134:135], v[164:165]
	v_pk_fma_f32 v[156:157], v[152:153], v[104:105], v[156:157]
	v_pk_fma_f32 v[158:159], v[152:153], v[112:113], v[158:159]
	v_pk_fma_f32 v[160:161], v[152:153], v[120:121], v[160:161]
	v_pk_fma_f32 v[162:163], v[152:153], v[128:129], v[162:163]
	v_pk_fma_f32 v[164:165], v[152:153], v[136:137], v[164:165]
	v_pk_fma_f32 v[156:157], v[154:155], v[106:107], v[156:157]
	v_pk_fma_f32 v[158:159], v[154:155], v[114:115], v[158:159]
	v_pk_fma_f32 v[160:161], v[154:155], v[122:123], v[160:161]
	v_pk_fma_f32 v[162:163], v[154:155], v[130:131], v[162:163]
	v_pk_fma_f32 v[164:165], v[154:155], v[138:139], v[164:165]
	ds_read_b128 v[100:103], v26 offset:1120
	ds_read_b128 v[104:107], v26 offset:1136
	ds_read_b128 v[108:111], v26 offset:1152
	ds_read_b128 v[112:115], v26 offset:1168
	ds_read_b128 v[116:119], v26 offset:1184
	ds_read_b128 v[120:123], v26 offset:1200
	ds_read_b128 v[124:127], v26 offset:1216
	ds_read_b128 v[128:131], v26 offset:1232
	ds_read_b128 v[132:135], v26 offset:1248
	ds_read_b128 v[136:139], v26 offset:1264
	s_waitcnt vmcnt(7)
; __device__ __forceinline__ void cb_item(const bf16_t* WT, int ldw, int K, int n0, const float* shift, float* out, int ostride, int lane) {
;     ...
;     for (int k8 = 0; k8 < K; k8 += 8) {
;         const u32x4 q = *(const u32x4*)(wp + k8);
;         float w[8];
; #pragma unroll
;         for (int e = 0; e < 4; ++e) { w[2 * e] = __uint_as_float(q[e] << 16); w[2 * e + 1] = __uint_as_float(q[e] & 0xffff0000u); }
; #pragma unroll
;         for (int b = 0; b < 5; ++b) { const float* sp = shift + (size_t)b * 9216 + k8;
; #pragma unroll
;             for (int e = 0; e < 8; ++e) a[b] += w[e] * sp[e]; }
;     }
	v_lshlrev_b32_e32 v148, 16, v52
	v_and_b32_e32 v149, 0xffff0000, v52
	v_lshlrev_b32_e32 v150, 16, v53
	v_and_b32_e32 v151, 0xffff0000, v53
	v_lshlrev_b32_e32 v152, 16, v54
	v_and_b32_e32 v153, 0xffff0000, v54
	v_lshlrev_b32_e32 v154, 16, v55
	v_and_b32_e32 v155, 0xffff0000, v55
	global_load_dwordx4 v[52:55], v25, s[34:35] offset:224
	s_waitcnt lgkmcnt(10)
	v_pk_fma_f32 v[156:157], v[148:149], v[60:61], v[156:157]
	v_pk_fma_f32 v[158:159], v[148:149], v[68:69], v[158:159]
	v_pk_fma_f32 v[160:161], v[148:149], v[76:77], v[160:161]
	v_pk_fma_f32 v[162:163], v[148:149], v[84:85], v[162:163]
	v_pk_fma_f32 v[164:165], v[148:149], v[92:93], v[164:165]
	v_pk_fma_f32 v[156:157], v[150:151], v[62:63], v[156:157]
	v_pk_fma_f32 v[158:159], v[150:151], v[70:71], v[158:159]
	v_pk_fma_f32 v[160:161], v[150:151], v[78:79], v[160:161]
	v_pk_fma_f32 v[162:163], v[150:151], v[86:87], v[162:163]
	v_pk_fma_f32 v[164:165], v[150:151], v[94:95], v[164:165]
	v_pk_fma_f32 v[156:157], v[152:153], v[64:65], v[156:157]
	v_pk_fma_f32 v[158:159], v[152:153], v[72:73], v[158:159]
	v_pk_fma_f32 v[160:161], v[152:153], v[80:81], v[160:161]
	v_pk_fma_f32 v[162:163], v[152:153], v[88:89], v[162:163]
	v_pk_fma_f32 v[164:165], v[152:153], v[96:97], v[164:165]
	v_pk_fma_f32 v[156:157], v[154:155], v[66:67], v[156:157]
	v_pk_fma_f32 v[158:159], v[154:155], v[74:75], v[158:159]
	v_pk_fma_f32 v[160:161], v[154:155], v[82:83], v[160:161]
	v_pk_fma_f32 v[162:163], v[154:155], v[90:91], v[162:163]
	v_pk_fma_f32 v[164:165], v[154:155], v[98:99], v[164:165]
	ds_read_b128 v[60:63], v26 offset:1280
	ds_read_b128 v[64:67], v26 offset:1296
	ds_read_b128 v[68:71], v26 offset:1312
	ds_read_b128 v[72:75], v26 offset:1328
	ds_read_b128 v[76:79], v26 offset:1344
	ds_read_b128 v[80:83], v26 offset:1360
	ds_read_b128 v[84:87], v26 offset:1376
	ds_read_b128 v[88:91], v26 offset:1392
	ds_read_b128 v[92:95], v26 offset:1408
	ds_read_b128 v[96:99], v26 offset:1424
	s_waitcnt vmcnt(7)
	v_lshlrev_b32_e32 v148, 16, v56
	v_and_b32_e32 v149, 0xffff0000, v56
	v_lshlrev_b32_e32 v150, 16, v57
	v_and_b32_e32 v151, 0xffff0000, v57
	v_lshlrev_b32_e32 v152, 16, v58
	v_and_b32_e32 v153, 0xffff0000, v58
	v_lshlrev_b32_e32 v154, 16, v59
	v_and_b32_e32 v155, 0xffff0000, v59
	global_load_dwordx4 v[56:59], v25, s[34:35] offset:240
	s_waitcnt lgkmcnt(10)
	v_pk_fma_f32 v[156:157], v[148:149], v[100:101], v[156:157]
	v_pk_fma_f32 v[158:159], v[148:149], v[108:109], v[158:159]
	v_pk_fma_f32 v[160:161], v[148:149], v[116:117], v[160:161]
	v_pk_fma_f32 v[162:163], v[148:149], v[124:125], v[162:163]
	v_pk_fma_f32 v[164:165], v[148:149], v[132:133], v[164:165]
	v_pk_fma_f32 v[156:157], v[150:151], v[102:103], v[156:157]
	v_pk_fma_f32 v[158:159], v[150:151], v[110:111], v[158:159]
	v_pk_fma_f32 v[160:161], v[150:151], v[118:119], v[160:161]
	v_pk_fma_f32 v[162:163], v[150:151], v[126:127], v[162:163]
	v_pk_fma_f32 v[164:165], v[150:151], v[134:135], v[164:165]
	v_pk_fma_f32 v[156:157], v[152:153], v[104:105], v[156:157]
	v_pk_fma_f32 v[158:159], v[152:153], v[112:113], v[158:159]
	v_pk_fma_f32 v[160:161], v[152:153], v[120:121], v[160:161]
	v_pk_fma_f32 v[162:163], v[152:153], v[128:129], v[162:163]
	v_pk_fma_f32 v[164:165], v[152:153], v[136:137], v[164:165]
	v_pk_fma_f32 v[156:157], v[154:155], v[106:107], v[156:157]
	v_pk_fma_f32 v[158:159], v[154:155], v[114:115], v[158:159]
	v_pk_fma_f32 v[160:161], v[154:155], v[122:123], v[160:161]
	v_pk_fma_f32 v[162:163], v[154:155], v[130:131], v[162:163]
	v_pk_fma_f32 v[164:165], v[154:155], v[138:139], v[164:165]
	v_add_u32_e32 v25, 0x80, v25
	v_add_u32_e32 v26, 0x500, v26
	s_add_i32 s41, s41, -1
	s_cmp_lg_u32 s41, 0
	s_cbranch_scc1 .Lcb1_loop_f_0
	s_waitcnt vmcnt(0) lgkmcnt(0)
	s_add_u32 s0, s36, 0x800
	s_addc_u32 s1, s37, 0
	global_load_dwordx4 v[28:31], v19, s[0:1]
	global_load_dwordx4 v[32:35], v19, s[0:1] offset:16
	s_add_u32 s0, s0, 0x9000
	s_addc_u32 s1, s1, 0
	global_load_dwordx4 v[36:39], v19, s[0:1]
	global_load_dwordx4 v[40:43], v19, s[0:1] offset:16
	s_add_u32 s0, s0, 0x9000
	s_addc_u32 s1, s1, 0
	global_load_dwordx4 v[44:47], v19, s[0:1]
	global_load_dwordx4 v[48:51], v19, s[0:1] offset:16
	s_add_u32 s0, s0, 0x9000
	s_addc_u32 s1, s1, 0
	global_load_dwordx4 v[52:55], v19, s[0:1]
	global_load_dwordx4 v[56:59], v19, s[0:1] offset:16
	s_add_u32 s0, s0, 0x9000
	s_addc_u32 s1, s1, 0
	global_load_dwordx4 v[140:143], v19, s[0:1]
	global_load_dwordx4 v[144:147], v19, s[0:1] offset:16
	s_waitcnt vmcnt(0)
	ds_write_b128 v18, v[28:31]
	ds_write_b128 v18, v[32:35] offset:16
	ds_write_b128 v18, v[36:39] offset:32
	ds_write_b128 v18, v[40:43] offset:48
	ds_write_b128 v18, v[44:47] offset:64
	ds_write_b128 v18, v[48:51] offset:80
	ds_write_b128 v18, v[52:55] offset:96
	ds_write_b128 v18, v[56:59] offset:112
	ds_write_b128 v18, v[140:143] offset:128
	ds_write_b128 v18, v[144:147] offset:144
	s_waitcnt lgkmcnt(0)
	v_add_u32_e32 v25, 0x400, v17
	v_mov_b32_e32 v26, v27
	global_load_dwordx4 v[28:31], v25, s[34:35]
	global_load_dwordx4 v[32:35], v25, s[34:35] offset:16
	global_load_dwordx4 v[36:39], v25, s[34:35] offset:32
	global_load_dwordx4 v[40:43], v25, s[34:35] offset:48
	global_load_dwordx4 v[44:47], v25, s[34:35] offset:64
	global_load_dwordx4 v[48:51], v25, s[34:35] offset:80
	global_load_dwordx4 v[52:55], v25, s[34:35] offset:96
	global_load_dwordx4 v[56:59], v25, s[34:35] offset:112
	ds_read_b128 v[60:63], v26
	ds_read_b128 v[64:67], v26 offset:16
	ds_read_b128 v[68:71], v26 offset:32
	ds_read_b128 v[72:75], v26 offset:48
	ds_read_b128 v[76:79], v26 offset:64
	ds_read_b128 v[80:83], v26 offset:80
	ds_read_b128 v[84:87], v26 offset:96
	ds_read_b128 v[88:91], v26 offset:112
	ds_read_b128 v[92:95], v26 offset:128
	ds_read_b128 v[96:99], v26 offset:144
	s_mov_b32 s41, 8
; __device__ __forceinline__ void cb_item(const bf16_t* WT, int ldw, int K, int n0, const float* shift, float* out, int ostride, int lane) {
;     ...
;     for (int k8 = 0; k8 < K; k8 += 8) {
;         const u32x4 q = *(const u32x4*)(wp + k8);
;         float w[8];
; #pragma unroll
;         for (int e = 0; e < 4; ++e) { w[2 * e] = __uint_as_float(q[e] << 16); w[2 * e + 1] = __uint_as_float(q[e] & 0xffff0000u); }
; #pragma unroll
;         for (int b = 0; b < 5; ++b) { const float* sp = shift + (size_t)b * 9216 + k8;
; #pragma unroll
;             for (int e = 0; e < 8; ++e) a[b] += w[e] * sp[e]; }
;     }
.Lcb1_loop_f_1:
	ds_read_b128 v[100:103], v26 offset:160
	ds_read_b128 v[104:107], v26 offset:176
	ds_read_b128 v[108:111], v26 offset:192
	ds_read_b128 v[112:115], v26 offset:208
	ds_read_b128 v[116:119], v26 offset:224
	ds_read_b128 v[120:123], v26 offset:240
	ds_read_b128 v[124:127], v26 offset:256
	ds_read_b128 v[128:131], v26 offset:272
	ds_read_b128 v[132:135], v26 offset:288
	ds_read_b128 v[136:139], v26 offset:304
	s_waitcnt vmcnt(7)
	v_lshlrev_b32_e32 v148, 16, v28
	v_and_b32_e32 v149, 0xffff0000, v28
	v_lshlrev_b32_e32 v150, 16, v29
	v_and_b32_e32 v151, 0xffff0000, v29
	v_lshlrev_b32_e32 v152, 16, v30
	v_and_b32_e32 v153, 0xffff0000, v30
	v_lshlrev_b32_e32 v154, 16, v31
	v_and_b32_e32 v155, 0xffff0000, v31
	global_load_dwordx4 v[28:31], v25, s[34:35] offset:128
	s_waitcnt lgkmcnt(10)
	v_pk_fma_f32 v[156:157], v[148:149], v[60:61], v[156:157]
	v_pk_fma_f32 v[158:159], v[148:149], v[68:69], v[158:159]
	v_pk_fma_f32 v[160:161], v[148:149], v[76:77], v[160:161]
	v_pk_fma_f32 v[162:163], v[148:149], v[84:85], v[162:163]
	v_pk_fma_f32 v[164:165], v[148:149], v[92:93], v[164:165]
	v_pk_fma_f32 v[156:157], v[150:151], v[62:63], v[156:157]
	v_pk_fma_f32 v[158:159], v[150:151], v[70:71], v[158:159]
	v_pk_fma_f32 v[160:161], v[150:151], v[78:79], v[160:161]
	v_pk_fma_f32 v[162:163], v[150:151], v[86:87], v[162:163]
	v_pk_fma_f32 v[164:165], v[150:151], v[94:95], v[164:165]
	v_pk_fma_f32 v[156:157], v[152:153], v[64:65], v[156:157]
	v_pk_fma_f32 v[158:159], v[152:153], v[72:73], v[158:159]
	v_pk_fma_f32 v[160:161], v[152:153], v[80:81], v[160:161]
	v_pk_fma_f32 v[162:163], v[152:153], v[88:89], v[162:163]
	v_pk_fma_f32 v[164:165], v[152:153], v[96:97], v[164:165]
	v_pk_fma_f32 v[156:157], v[154:155], v[66:67], v[156:157]
	v_pk_fma_f32 v[158:159], v[154:155], v[74:75], v[158:159]
	v_pk_fma_f32 v[160:161], v[154:155], v[82:83], v[160:161]
	v_pk_fma_f32 v[162:163], v[154:155], v[90:91], v[162:163]
	v_pk_fma_f32 v[164:165], v[154:155], v[98:99], v[164:165]
	ds_read_b128 v[60:63], v26 offset:320
	ds_read_b128 v[64:67], v26 offset:336
	ds_read_b128 v[68:71], v26 offset:352
	ds_read_b128 v[72:75], v26 offset:368
	ds_read_b128 v[76:79], v26 offset:384
	ds_read_b128 v[80:83], v26 offset:400
	ds_read_b128 v[84:87], v26 offset:416
	ds_read_b128 v[88:91], v26 offset:432
	ds_read_b128 v[92:95], v26 offset:448
	ds_read_b128 v[96:99], v26 offset:464
	s_waitcnt vmcnt(7)
	v_lshlrev_b32_e32 v148, 16, v32
	v_and_b32_e32 v149, 0xffff0000, v32
	v_lshlrev_b32_e32 v150, 16, v33
	v_and_b32_e32 v151, 0xffff0000, v33
	v_lshlrev_b32_e32 v152, 16, v34
	v_and_b32_e32 v153, 0xffff0000, v34
	v_lshlrev_b32_e32 v154, 16, v35
	v_and_b32_e32 v155, 0xffff0000, v35
	global_load_dwordx4 v[32:35], v25, s[34:35] offset:144
	s_waitcnt lgkmcnt(10)
	v_pk_fma_f32 v[156:157], v[148:149], v[100:101], v[156:157]
	v_pk_fma_f32 v[158:159], v[148:149], v[108:109], v[158:159]
	v_pk_fma_f32 v[160:161], v[148:149], v[116:117], v[160:161]
	v_pk_fma_f32 v[162:163], v[148:149], v[124:125], v[162:163]
	v_pk_fma_f32 v[164:165], v[148:149], v[132:133], v[164:165]
	v_pk_fma_f32 v[156:157], v[150:151], v[102:103], v[156:157]
	v_pk_fma_f32 v[158:159], v[150:151], v[110:111], v[158:159]
	v_pk_fma_f32 v[160:161], v[150:151], v[118:119], v[160:161]
	v_pk_fma_f32 v[162:163], v[150:151], v[126:127], v[162:163]
	v_pk_fma_f32 v[164:165], v[150:151], v[134:135], v[164:165]
	v_pk_fma_f32 v[156:157], v[152:153], v[104:105], v[156:157]
	v_pk_fma_f32 v[158:159], v[152:153], v[112:113], v[158:159]
	v_pk_fma_f32 v[160:161], v[152:153], v[120:121], v[160:161]
	v_pk_fma_f32 v[162:163], v[152:153], v[128:129], v[162:163]
	v_pk_fma_f32 v[164:165], v[152:153], v[136:137], v[164:165]
	v_pk_fma_f32 v[156:157], v[154:155], v[106:107], v[156:157]
	v_pk_fma_f32 v[158:159], v[154:155], v[114:115], v[158:159]
	v_pk_fma_f32 v[160:161], v[154:155], v[122:123], v[160:161]
	v_pk_fma_f32 v[162:163], v[154:155], v[130:131], v[162:163]
	v_pk_fma_f32 v[164:165], v[154:155], v[138:139], v[164:165]
	ds_read_b128 v[100:103], v26 offset:480
	ds_read_b128 v[104:107], v26 offset:496
	ds_read_b128 v[108:111], v26 offset:512
	ds_read_b128 v[112:115], v26 offset:528
	ds_read_b128 v[116:119], v26 offset:544
	ds_read_b128 v[120:123], v26 offset:560
	ds_read_b128 v[124:127], v26 offset:576
	ds_read_b128 v[128:131], v26 offset:592
	ds_read_b128 v[132:135], v26 offset:608
	ds_read_b128 v[136:139], v26 offset:624
	s_waitcnt vmcnt(7)
	v_lshlrev_b32_e32 v148, 16, v36
	v_and_b32_e32 v149, 0xffff0000, v36
	v_lshlrev_b32_e32 v150, 16, v37
	v_and_b32_e32 v151, 0xffff0000, v37
	v_lshlrev_b32_e32 v152, 16, v38
	v_and_b32_e32 v153, 0xffff0000, v38
	v_lshlrev_b32_e32 v154, 16, v39
	v_and_b32_e32 v155, 0xffff0000, v39
	global_load_dwordx4 v[36:39], v25, s[34:35] offset:160
	s_waitcnt lgkmcnt(10)
	v_pk_fma_f32 v[156:157], v[148:149], v[60:61], v[156:157]
	v_pk_fma_f32 v[158:159], v[148:149], v[68:69], v[158:159]
	v_pk_fma_f32 v[160:161], v[148:149], v[76:77], v[160:161]
	v_pk_fma_f32 v[162:163], v[148:149], v[84:85], v[162:163]
	v_pk_fma_f32 v[164:165], v[148:149], v[92:93], v[164:165]
	v_pk_fma_f32 v[156:157], v[150:151], v[62:63], v[156:157]
	v_pk_fma_f32 v[158:159], v[150:151], v[70:71], v[158:159]
	v_pk_fma_f32 v[160:161], v[150:151], v[78:79], v[160:161]
	v_pk_fma_f32 v[162:163], v[150:151], v[86:87], v[162:163]
	v_pk_fma_f32 v[164:165], v[150:151], v[94:95], v[164:165]
	v_pk_fma_f32 v[156:157], v[152:153], v[64:65], v[156:157]
	v_pk_fma_f32 v[158:159], v[152:153], v[72:73], v[158:159]
	v_pk_fma_f32 v[160:161], v[152:153], v[80:81], v[160:161]
	v_pk_fma_f32 v[162:163], v[152:153], v[88:89], v[162:163]
	v_pk_fma_f32 v[164:165], v[152:153], v[96:97], v[164:165]
	v_pk_fma_f32 v[156:157], v[154:155], v[66:67], v[156:157]
	v_pk_fma_f32 v[158:159], v[154:155], v[74:75], v[158:159]
	v_pk_fma_f32 v[160:161], v[154:155], v[82:83], v[160:161]
	v_pk_fma_f32 v[162:163], v[154:155], v[90:91], v[162:163]
	v_pk_fma_f32 v[164:165], v[154:155], v[98:99], v[164:165]
	ds_read_b128 v[60:63], v26 offset:640
	ds_read_b128 v[64:67], v26 offset:656
	ds_read_b128 v[68:71], v26 offset:672
	ds_read_b128 v[72:75], v26 offset:688
	ds_read_b128 v[76:79], v26 offset:704
	ds_read_b128 v[80:83], v26 offset:720
	ds_read_b128 v[84:87], v26 offset:736
	ds_read_b128 v[88:91], v26 offset:752
	ds_read_b128 v[92:95], v26 offset:768
	ds_read_b128 v[96:99], v26 offset:784
	s_waitcnt vmcnt(7)
; __device__ __forceinline__ void cb_item(const bf16_t* WT, int ldw, int K, int n0, const float* shift, float* out, int ostride, int lane) {
;     ...
;     for (int k8 = 0; k8 < K; k8 += 8) {
;         const u32x4 q = *(const u32x4*)(wp + k8);
;         float w[8];
; #pragma unroll
;         for (int e = 0; e < 4; ++e) { w[2 * e] = __uint_as_float(q[e] << 16); w[2 * e + 1] = __uint_as_float(q[e] & 0xffff0000u); }
; #pragma unroll
;         for (int b = 0; b < 5; ++b) { const float* sp = shift + (size_t)b * 9216 + k8;
; #pragma unroll
;             for (int e = 0; e < 8; ++e) a[b] += w[e] * sp[e]; }
;     }
	v_lshlrev_b32_e32 v148, 16, v40
	v_and_b32_e32 v149, 0xffff0000, v40
	v_lshlrev_b32_e32 v150, 16, v41
	v_and_b32_e32 v151, 0xffff0000, v41
	v_lshlrev_b32_e32 v152, 16, v42
	v_and_b32_e32 v153, 0xffff0000, v42
	v_lshlrev_b32_e32 v154, 16, v43
	v_and_b32_e32 v155, 0xffff0000, v43
	global_load_dwordx4 v[40:43], v25, s[34:35] offset:176
	s_waitcnt lgkmcnt(10)
	v_pk_fma_f32 v[156:157], v[148:149], v[100:101], v[156:157]
	v_pk_fma_f32 v[158:159], v[148:149], v[108:109], v[158:159]
	v_pk_fma_f32 v[160:161], v[148:149], v[116:117], v[160:161]
	v_pk_fma_f32 v[162:163], v[148:149], v[124:125], v[162:163]
	v_pk_fma_f32 v[164:165], v[148:149], v[132:133], v[164:165]
	v_pk_fma_f32 v[156:157], v[150:151], v[102:103], v[156:157]
	v_pk_fma_f32 v[158:159], v[150:151], v[110:111], v[158:159]
	v_pk_fma_f32 v[160:161], v[150:151], v[118:119], v[160:161]
	v_pk_fma_f32 v[162:163], v[150:151], v[126:127], v[162:163]
	v_pk_fma_f32 v[164:165], v[150:151], v[134:135], v[164:165]
	v_pk_fma_f32 v[156:157], v[152:153], v[104:105], v[156:157]
	v_pk_fma_f32 v[158:159], v[152:153], v[112:113], v[158:159]
	v_pk_fma_f32 v[160:161], v[152:153], v[120:121], v[160:161]
	v_pk_fma_f32 v[162:163], v[152:153], v[128:129], v[162:163]
	v_pk_fma_f32 v[164:165], v[152:153], v[136:137], v[164:165]
	v_pk_fma_f32 v[156:157], v[154:155], v[106:107], v[156:157]
	v_pk_fma_f32 v[158:159], v[154:155], v[114:115], v[158:159]
	v_pk_fma_f32 v[160:161], v[154:155], v[122:123], v[160:161]
	v_pk_fma_f32 v[162:163], v[154:155], v[130:131], v[162:163]
	v_pk_fma_f32 v[164:165], v[154:155], v[138:139], v[164:165]
	ds_read_b128 v[100:103], v26 offset:800
	ds_read_b128 v[104:107], v26 offset:816
	ds_read_b128 v[108:111], v26 offset:832
	ds_read_b128 v[112:115], v26 offset:848
	ds_read_b128 v[116:119], v26 offset:864
	ds_read_b128 v[120:123], v26 offset:880
	ds_read_b128 v[124:127], v26 offset:896
	ds_read_b128 v[128:131], v26 offset:912
	ds_read_b128 v[132:135], v26 offset:928
	ds_read_b128 v[136:139], v26 offset:944
	s_waitcnt vmcnt(7)
	v_lshlrev_b32_e32 v148, 16, v44
	v_and_b32_e32 v149, 0xffff0000, v44
	v_lshlrev_b32_e32 v150, 16, v45
	v_and_b32_e32 v151, 0xffff0000, v45
	v_lshlrev_b32_e32 v152, 16, v46
	v_and_b32_e32 v153, 0xffff0000, v46
	v_lshlrev_b32_e32 v154, 16, v47
	v_and_b32_e32 v155, 0xffff0000, v47
	global_load_dwordx4 v[44:47], v25, s[34:35] offset:192
	s_waitcnt lgkmcnt(10)
	v_pk_fma_f32 v[156:157], v[148:149], v[60:61], v[156:157]
	v_pk_fma_f32 v[158:159], v[148:149], v[68:69], v[158:159]
	v_pk_fma_f32 v[160:161], v[148:149], v[76:77], v[160:161]
	v_pk_fma_f32 v[162:163], v[148:149], v[84:85], v[162:163]
	v_pk_fma_f32 v[164:165], v[148:149], v[92:93], v[164:165]
	v_pk_fma_f32 v[156:157], v[150:151], v[62:63], v[156:157]
	v_pk_fma_f32 v[158:159], v[150:151], v[70:71], v[158:159]
	v_pk_fma_f32 v[160:161], v[150:151], v[78:79], v[160:161]
	v_pk_fma_f32 v[162:163], v[150:151], v[86:87], v[162:163]
	v_pk_fma_f32 v[164:165], v[150:151], v[94:95], v[164:165]
	v_pk_fma_f32 v[156:157], v[152:153], v[64:65], v[156:157]
	v_pk_fma_f32 v[158:159], v[152:153], v[72:73], v[158:159]
	v_pk_fma_f32 v[160:161], v[152:153], v[80:81], v[160:161]
	v_pk_fma_f32 v[162:163], v[152:153], v[88:89], v[162:163]
	v_pk_fma_f32 v[164:165], v[152:153], v[96:97], v[164:165]
	v_pk_fma_f32 v[156:157], v[154:155], v[66:67], v[156:157]
	v_pk_fma_f32 v[158:159], v[154:155], v[74:75], v[158:159]
	v_pk_fma_f32 v[160:161], v[154:155], v[82:83], v[160:161]
	v_pk_fma_f32 v[162:163], v[154:155], v[90:91], v[162:163]
	v_pk_fma_f32 v[164:165], v[154:155], v[98:99], v[164:165]
	ds_read_b128 v[60:63], v26 offset:960
	ds_read_b128 v[64:67], v26 offset:976
	ds_read_b128 v[68:71], v26 offset:992
	ds_read_b128 v[72:75], v26 offset:1008
	ds_read_b128 v[76:79], v26 offset:1024
	ds_read_b128 v[80:83], v26 offset:1040
	ds_read_b128 v[84:87], v26 offset:1056
	ds_read_b128 v[88:91], v26 offset:1072
	ds_read_b128 v[92:95], v26 offset:1088
	ds_read_b128 v[96:99], v26 offset:1104
	s_waitcnt vmcnt(7)
	v_lshlrev_b32_e32 v148, 16, v48
	v_and_b32_e32 v149, 0xffff0000, v48
	v_lshlrev_b32_e32 v150, 16, v49
	v_and_b32_e32 v151, 0xffff0000, v49
	v_lshlrev_b32_e32 v152, 16, v50
	v_and_b32_e32 v153, 0xffff0000, v50
	v_lshlrev_b32_e32 v154, 16, v51
	v_and_b32_e32 v155, 0xffff0000, v51
	global_load_dwordx4 v[48:51], v25, s[34:35] offset:208
	s_waitcnt lgkmcnt(10)
	v_pk_fma_f32 v[156:157], v[148:149], v[100:101], v[156:157]
	v_pk_fma_f32 v[158:159], v[148:149], v[108:109], v[158:159]
	v_pk_fma_f32 v[160:161], v[148:149], v[116:117], v[160:161]
	v_pk_fma_f32 v[162:163], v[148:149], v[124:125], v[162:163]
	v_pk_fma_f32 v[164:165], v[148:149], v[132:133], v[164:165]
	v_pk_fma_f32 v[156:157], v[150:151], v[102:103], v[156:157]
	v_pk_fma_f32 v[158:159], v[150:151], v[110:111], v[158:159]
	v_pk_fma_f32 v[160:161], v[150:151], v[118:119], v[160:161]
	v_pk_fma_f32 v[162:163], v[150:151], v[126:127], v[162:163]
	v_pk_fma_f32 v[164:165], v[150:151], v[134:135], v[164:165]
	v_pk_fma_f32 v[156:157], v[152:153], v[104:105], v[156:157]
	v_pk_fma_f32 v[158:159], v[152:153], v[112:113], v[158:159]
	v_pk_fma_f32 v[160:161], v[152:153], v[120:121], v[160:161]
	v_pk_fma_f32 v[162:163], v[152:153], v[128:129], v[162:163]
	v_pk_fma_f32 v[164:165], v[152:153], v[136:137], v[164:165]
	v_pk_fma_f32 v[156:157], v[154:155], v[106:107], v[156:157]
	v_pk_fma_f32 v[158:159], v[154:155], v[114:115], v[158:159]
	v_pk_fma_f32 v[160:161], v[154:155], v[122:123], v[160:161]
	v_pk_fma_f32 v[162:163], v[154:155], v[130:131], v[162:163]
	v_pk_fma_f32 v[164:165], v[154:155], v[138:139], v[164:165]
	ds_read_b128 v[100:103], v26 offset:1120
	ds_read_b128 v[104:107], v26 offset:1136
	ds_read_b128 v[108:111], v26 offset:1152
	ds_read_b128 v[112:115], v26 offset:1168
	ds_read_b128 v[116:119], v26 offset:1184
	ds_read_b128 v[120:123], v26 offset:1200
	ds_read_b128 v[124:127], v26 offset:1216
	ds_read_b128 v[128:131], v26 offset:1232
	ds_read_b128 v[132:135], v26 offset:1248
	ds_read_b128 v[136:139], v26 offset:1264
	s_waitcnt vmcnt(7)
; __device__ __forceinline__ void cb_item(const bf16_t* WT, int ldw, int K, int n0, const float* shift, float* out, int ostride, int lane) {
;     ...
;     for (int k8 = 0; k8 < K; k8 += 8) {
;         const u32x4 q = *(const u32x4*)(wp + k8);
;         float w[8];
; #pragma unroll
;         for (int e = 0; e < 4; ++e) { w[2 * e] = __uint_as_float(q[e] << 16); w[2 * e + 1] = __uint_as_float(q[e] & 0xffff0000u); }
; #pragma unroll
;         for (int b = 0; b < 5; ++b) { const float* sp = shift + (size_t)b * 9216 + k8;
; #pragma unroll
;             for (int e = 0; e < 8; ++e) a[b] += w[e] * sp[e]; }
;     }
; #pragma unroll
;     for (int b = 0; b < 5; ++b) out[(size_t)b * ostride + n0 + lane] = a[b];
	v_lshlrev_b32_e32 v148, 16, v52
	v_and_b32_e32 v149, 0xffff0000, v52
	v_lshlrev_b32_e32 v150, 16, v53
	v_and_b32_e32 v151, 0xffff0000, v53
	v_lshlrev_b32_e32 v152, 16, v54
	v_and_b32_e32 v153, 0xffff0000, v54
	v_lshlrev_b32_e32 v154, 16, v55
	v_and_b32_e32 v155, 0xffff0000, v55
	global_load_dwordx4 v[52:55], v25, s[34:35] offset:224
	s_waitcnt lgkmcnt(10)
	v_pk_fma_f32 v[156:157], v[148:149], v[60:61], v[156:157]
	v_pk_fma_f32 v[158:159], v[148:149], v[68:69], v[158:159]
	v_pk_fma_f32 v[160:161], v[148:149], v[76:77], v[160:161]
	v_pk_fma_f32 v[162:163], v[148:149], v[84:85], v[162:163]
	v_pk_fma_f32 v[164:165], v[148:149], v[92:93], v[164:165]
	v_pk_fma_f32 v[156:157], v[150:151], v[62:63], v[156:157]
	v_pk_fma_f32 v[158:159], v[150:151], v[70:71], v[158:159]
	v_pk_fma_f32 v[160:161], v[150:151], v[78:79], v[160:161]
	v_pk_fma_f32 v[162:163], v[150:151], v[86:87], v[162:163]
	v_pk_fma_f32 v[164:165], v[150:151], v[94:95], v[164:165]
	v_pk_fma_f32 v[156:157], v[152:153], v[64:65], v[156:157]
	v_pk_fma_f32 v[158:159], v[152:153], v[72:73], v[158:159]
	v_pk_fma_f32 v[160:161], v[152:153], v[80:81], v[160:161]
	v_pk_fma_f32 v[162:163], v[152:153], v[88:89], v[162:163]
	v_pk_fma_f32 v[164:165], v[152:153], v[96:97], v[164:165]
	v_pk_fma_f32 v[156:157], v[154:155], v[66:67], v[156:157]
	v_pk_fma_f32 v[158:159], v[154:155], v[74:75], v[158:159]
	v_pk_fma_f32 v[160:161], v[154:155], v[82:83], v[160:161]
	v_pk_fma_f32 v[162:163], v[154:155], v[90:91], v[162:163]
	v_pk_fma_f32 v[164:165], v[154:155], v[98:99], v[164:165]
	ds_read_b128 v[60:63], v26 offset:1280
	ds_read_b128 v[64:67], v26 offset:1296
	ds_read_b128 v[68:71], v26 offset:1312
	ds_read_b128 v[72:75], v26 offset:1328
	ds_read_b128 v[76:79], v26 offset:1344
	ds_read_b128 v[80:83], v26 offset:1360
	ds_read_b128 v[84:87], v26 offset:1376
	ds_read_b128 v[88:91], v26 offset:1392
	ds_read_b128 v[92:95], v26 offset:1408
	ds_read_b128 v[96:99], v26 offset:1424
	s_waitcnt vmcnt(7)
	v_lshlrev_b32_e32 v148, 16, v56
	v_and_b32_e32 v149, 0xffff0000, v56
	v_lshlrev_b32_e32 v150, 16, v57
	v_and_b32_e32 v151, 0xffff0000, v57
	v_lshlrev_b32_e32 v152, 16, v58
	v_and_b32_e32 v153, 0xffff0000, v58
	v_lshlrev_b32_e32 v154, 16, v59
	v_and_b32_e32 v155, 0xffff0000, v59
	global_load_dwordx4 v[56:59], v25, s[34:35] offset:240
	s_waitcnt lgkmcnt(10)
	v_pk_fma_f32 v[156:157], v[148:149], v[100:101], v[156:157]
	v_pk_fma_f32 v[158:159], v[148:149], v[108:109], v[158:159]
	v_pk_fma_f32 v[160:161], v[148:149], v[116:117], v[160:161]
	v_pk_fma_f32 v[162:163], v[148:149], v[124:125], v[162:163]
	v_pk_fma_f32 v[164:165], v[148:149], v[132:133], v[164:165]
	v_pk_fma_f32 v[156:157], v[150:151], v[102:103], v[156:157]
	v_pk_fma_f32 v[158:159], v[150:151], v[110:111], v[158:159]
	v_pk_fma_f32 v[160:161], v[150:151], v[118:119], v[160:161]
	v_pk_fma_f32 v[162:163], v[150:151], v[126:127], v[162:163]
	v_pk_fma_f32 v[164:165], v[150:151], v[134:135], v[164:165]
	v_pk_fma_f32 v[156:157], v[152:153], v[104:105], v[156:157]
	v_pk_fma_f32 v[158:159], v[152:153], v[112:113], v[158:159]
	v_pk_fma_f32 v[160:161], v[152:153], v[120:121], v[160:161]
	v_pk_fma_f32 v[162:163], v[152:153], v[128:129], v[162:163]
	v_pk_fma_f32 v[164:165], v[152:153], v[136:137], v[164:165]
	v_pk_fma_f32 v[156:157], v[154:155], v[106:107], v[156:157]
	v_pk_fma_f32 v[158:159], v[154:155], v[114:115], v[158:159]
	v_pk_fma_f32 v[160:161], v[154:155], v[122:123], v[160:161]
	v_pk_fma_f32 v[162:163], v[154:155], v[130:131], v[162:163]
	v_pk_fma_f32 v[164:165], v[154:155], v[138:139], v[164:165]
	v_add_u32_e32 v25, 0x80, v25
	v_add_u32_e32 v26, 0x500, v26
	s_add_i32 s41, s41, -1
	s_cmp_lg_u32 s41, 0
	s_cbranch_scc1 .Lcb1_loop_f_1
	s_waitcnt vmcnt(0) lgkmcnt(0)
	s_mov_b64 s[0:1], s[38:39]
	v_lshlrev_b32_e32 v27, 2, v16
	v_add_f32_e32 v20, v156, v157
	v_add_f32_e32 v21, v158, v159
	v_add_f32_e32 v22, v160, v161
	v_add_f32_e32 v23, v162, v163
	v_add_f32_e32 v24, v164, v165
	global_store_dword v27, v20, s[0:1]
	s_add_u32 s0, s0, s40
	s_addc_u32 s1, s1, 0
	global_store_dword v27, v21, s[0:1]
	s_add_u32 s0, s0, s40
	s_addc_u32 s1, s1, 0
	global_store_dword v27, v22, s[0:1]
	s_add_u32 s0, s0, s40
	s_addc_u32 s1, s1, 0
	global_store_dword v27, v23, s[0:1]
	s_add_u32 s0, s0, s40
	s_addc_u32 s1, s1, 0
	global_store_dword v27, v24, s[0:1]
	s_branch .Lph2_cbfin
; __device__ __forceinline__ void cb_item(const bf16_t* WT, int ldw, int K, int n0, const float* shift, float* out, int ostride, int lane) {
;     const bf16_t* wp = WT + (size_t)(n0 + lane) * ldw;
;     float a[5] = {0.f, 0.f, 0.f, 0.f, 0.f};
; #pragma unroll 4
;     for (int k8 = 0; k8 < K; k8 += 8) {
;         const u32x4 q = *(const u32x4*)(wp + k8);
;         float w[8];
; #pragma unroll
;         for (int e = 0; e < 4; ++e) { w[2 * e] = __uint_as_float(q[e] << 16); w[2 * e + 1] = __uint_as_float(q[e] & 0xffff0000u); }
; #pragma unroll
;         for (int b = 0; b < 5; ++b) { const float* sp = shift + (size_t)b * 9216 + k8;
; #pragma unroll
;             for (int e = 0; e < 8; ++e) a[b] += w[e] * sp[e]; }
;     }
; __device__ __forceinline__ void cb_tables(const Params& p) {
;     ...
;         else { const int e = it - 392, gr = e >> 3, ch = e & 7;
;             cb_item((const bf16_t*)(ws + WS_DFTC), 256, 256, ch * 64, MOD + (size_t)5 * 9216 + 3 * 1024 + gr * 256, (float*)(ws + WS_CBD) + gr * 512, 2048, lane); }
.Lph2_w1_dft:
	s_cmpk_ge_u32 s84, 0xa8
	s_cbranch_scc1 .Lph2_cbfin
	s_sub_i32 s43, s84, 0x88
	s_lshr_b32 s42, s43, 3
	s_and_b32 s43, s43, 7
	s_lshl_b32 s45, s43, 15
	s_add_u32 s45, s45, 0x4d00000
	s_add_u32 s34, s80, s45
	s_addc_u32 s35, s81, 0
	s_lshl_b32 s45, s42, 10
	s_add_u32 s45, s45, 0x30000
	s_add_u32 s36, s80, s45
	s_addc_u32 s37, s81, 0
	s_lshl_b32 s45, s42, 11
	s_lshl_b32 s0, s43, 8
	s_add_u32 s45, s45, s0
	s_add_u32 s45, s45, 0x17a800
	s_add_u32 s38, s80, s45
	s_addc_u32 s39, s81, 0
	s_movk_i32 s40, 0x2000
	v_and_b32_e32 v16, 63, v176
	v_lshlrev_b32_e32 v17, 9, v16
	s_lshl_b32 s45, s44, 14
	v_mov_b32_e32 v27, s45
	v_mul_u32_u24_e32 v18, 0xa0, v16
	v_add_u32_e32 v18, s45, v18
	v_lshlrev_b32_e32 v19, 5, v16
	v_mov_b32_e32 v156, 0
	v_mov_b32_e32 v157, 0
	v_mov_b32_e32 v158, 0
	v_mov_b32_e32 v159, 0
	v_mov_b32_e32 v160, 0
	v_mov_b32_e32 v161, 0
	v_mov_b32_e32 v162, 0
	v_mov_b32_e32 v163, 0
	v_mov_b32_e32 v164, 0
	v_mov_b32_e32 v165, 0
	s_add_u32 s0, s36, 0x0
	s_addc_u32 s1, s37, 0
	global_load_dwordx4 v[28:31], v19, s[0:1]
	global_load_dwordx4 v[32:35], v19, s[0:1] offset:16
	s_add_u32 s0, s0, 0x9000
	s_addc_u32 s1, s1, 0
	global_load_dwordx4 v[36:39], v19, s[0:1]
	global_load_dwordx4 v[40:43], v19, s[0:1] offset:16
	s_add_u32 s0, s0, 0x9000
	s_addc_u32 s1, s1, 0
	global_load_dwordx4 v[44:47], v19, s[0:1]
	global_load_dwordx4 v[48:51], v19, s[0:1] offset:16
	s_add_u32 s0, s0, 0x9000
	s_addc_u32 s1, s1, 0
	global_load_dwordx4 v[52:55], v19, s[0:1]
	global_load_dwordx4 v[56:59], v19, s[0:1] offset:16
	s_add_u32 s0, s0, 0x9000
	s_addc_u32 s1, s1, 0
	global_load_dwordx4 v[140:143], v19, s[0:1]
	global_load_dwordx4 v[144:147], v19, s[0:1] offset:16
	s_waitcnt vmcnt(0)
	ds_write_b128 v18, v[28:31]
	ds_write_b128 v18, v[32:35] offset:16
	ds_write_b128 v18, v[36:39] offset:32
	ds_write_b128 v18, v[40:43] offset:48
	ds_write_b128 v18, v[44:47] offset:64
	ds_write_b128 v18, v[48:51] offset:80
	ds_write_b128 v18, v[52:55] offset:96
	ds_write_b128 v18, v[56:59] offset:112
	ds_write_b128 v18, v[140:143] offset:128
	ds_write_b128 v18, v[144:147] offset:144
	s_waitcnt lgkmcnt(0)
	v_add_u32_e32 v25, 0x0, v17
	v_mov_b32_e32 v26, v27
	global_load_dwordx4 v[28:31], v25, s[34:35]
	global_load_dwordx4 v[32:35], v25, s[34:35] offset:16
	global_load_dwordx4 v[36:39], v25, s[34:35] offset:32
	global_load_dwordx4 v[40:43], v25, s[34:35] offset:48
	global_load_dwordx4 v[44:47], v25, s[34:35] offset:64
	global_load_dwordx4 v[48:51], v25, s[34:35] offset:80
	global_load_dwordx4 v[52:55], v25, s[34:35] offset:96
	global_load_dwordx4 v[56:59], v25, s[34:35] offset:112
	ds_read_b128 v[60:63], v26
	ds_read_b128 v[64:67], v26 offset:16
	ds_read_b128 v[68:71], v26 offset:32
	ds_read_b128 v[72:75], v26 offset:48
	ds_read_b128 v[76:79], v26 offset:64
	ds_read_b128 v[80:83], v26 offset:80
	ds_read_b128 v[84:87], v26 offset:96
	ds_read_b128 v[88:91], v26 offset:112
	ds_read_b128 v[92:95], v26 offset:128
	ds_read_b128 v[96:99], v26 offset:144
	s_mov_b32 s41, 4
.Lcb1_loop_d_0:
	ds_read_b128 v[100:103], v26 offset:160
	ds_read_b128 v[104:107], v26 offset:176
	ds_read_b128 v[108:111], v26 offset:192
	ds_read_b128 v[112:115], v26 offset:208
	ds_read_b128 v[116:119], v26 offset:224
	ds_read_b128 v[120:123], v26 offset:240
	ds_read_b128 v[124:127], v26 offset:256
	ds_read_b128 v[128:131], v26 offset:272
	ds_read_b128 v[132:135], v26 offset:288
	ds_read_b128 v[136:139], v26 offset:304
	s_waitcnt vmcnt(7)
	v_lshlrev_b32_e32 v148, 16, v28
	v_and_b32_e32 v149, 0xffff0000, v28
	v_lshlrev_b32_e32 v150, 16, v29
	v_and_b32_e32 v151, 0xffff0000, v29
	v_lshlrev_b32_e32 v152, 16, v30
	v_and_b32_e32 v153, 0xffff0000, v30
	v_lshlrev_b32_e32 v154, 16, v31
	v_and_b32_e32 v155, 0xffff0000, v31
	global_load_dwordx4 v[28:31], v25, s[34:35] offset:128
	s_waitcnt lgkmcnt(10)
	v_pk_fma_f32 v[156:157], v[148:149], v[60:61], v[156:157]
	v_pk_fma_f32 v[158:159], v[148:149], v[68:69], v[158:159]
	v_pk_fma_f32 v[160:161], v[148:149], v[76:77], v[160:161]
	v_pk_fma_f32 v[162:163], v[148:149], v[84:85], v[162:163]
	v_pk_fma_f32 v[164:165], v[148:149], v[92:93], v[164:165]
	v_pk_fma_f32 v[156:157], v[150:151], v[62:63], v[156:157]
	v_pk_fma_f32 v[158:159], v[150:151], v[70:71], v[158:159]
	v_pk_fma_f32 v[160:161], v[150:151], v[78:79], v[160:161]
	v_pk_fma_f32 v[162:163], v[150:151], v[86:87], v[162:163]
	v_pk_fma_f32 v[164:165], v[150:151], v[94:95], v[164:165]
	v_pk_fma_f32 v[156:157], v[152:153], v[64:65], v[156:157]
	v_pk_fma_f32 v[158:159], v[152:153], v[72:73], v[158:159]
	v_pk_fma_f32 v[160:161], v[152:153], v[80:81], v[160:161]
	v_pk_fma_f32 v[162:163], v[152:153], v[88:89], v[162:163]
	v_pk_fma_f32 v[164:165], v[152:153], v[96:97], v[164:165]
	v_pk_fma_f32 v[156:157], v[154:155], v[66:67], v[156:157]
	v_pk_fma_f32 v[158:159], v[154:155], v[74:75], v[158:159]
	v_pk_fma_f32 v[160:161], v[154:155], v[82:83], v[160:161]
	v_pk_fma_f32 v[162:163], v[154:155], v[90:91], v[162:163]
	v_pk_fma_f32 v[164:165], v[154:155], v[98:99], v[164:165]
	ds_read_b128 v[60:63], v26 offset:320
	ds_read_b128 v[64:67], v26 offset:336
	ds_read_b128 v[68:71], v26 offset:352
	ds_read_b128 v[72:75], v26 offset:368
	ds_read_b128 v[76:79], v26 offset:384
	ds_read_b128 v[80:83], v26 offset:400
	ds_read_b128 v[84:87], v26 offset:416
	ds_read_b128 v[88:91], v26 offset:432
	ds_read_b128 v[92:95], v26 offset:448
	ds_read_b128 v[96:99], v26 offset:464
	s_waitcnt vmcnt(7)
	v_lshlrev_b32_e32 v148, 16, v32
	v_and_b32_e32 v149, 0xffff0000, v32
	v_lshlrev_b32_e32 v150, 16, v33
	v_and_b32_e32 v151, 0xffff0000, v33
	v_lshlrev_b32_e32 v152, 16, v34
	v_and_b32_e32 v153, 0xffff0000, v34
	v_lshlrev_b32_e32 v154, 16, v35
	v_and_b32_e32 v155, 0xffff0000, v35
	global_load_dwordx4 v[32:35], v25, s[34:35] offset:144
	s_waitcnt lgkmcnt(10)
; __device__ __forceinline__ void cb_item(const bf16_t* WT, int ldw, int K, int n0, const float* shift, float* out, int ostride, int lane) {
;     ...
;     for (int k8 = 0; k8 < K; k8 += 8) {
;         const u32x4 q = *(const u32x4*)(wp + k8);
;         float w[8];
; #pragma unroll
;         for (int e = 0; e < 4; ++e) { w[2 * e] = __uint_as_float(q[e] << 16); w[2 * e + 1] = __uint_as_float(q[e] & 0xffff0000u); }
; #pragma unroll
;         for (int b = 0; b < 5; ++b) { const float* sp = shift + (size_t)b * 9216 + k8;
; #pragma unroll
;             for (int e = 0; e < 8; ++e) a[b] += w[e] * sp[e]; }
;     }
	v_pk_fma_f32 v[156:157], v[148:149], v[100:101], v[156:157]
	v_pk_fma_f32 v[158:159], v[148:149], v[108:109], v[158:159]
	v_pk_fma_f32 v[160:161], v[148:149], v[116:117], v[160:161]
	v_pk_fma_f32 v[162:163], v[148:149], v[124:125], v[162:163]
	v_pk_fma_f32 v[164:165], v[148:149], v[132:133], v[164:165]
	v_pk_fma_f32 v[156:157], v[150:151], v[102:103], v[156:157]
	v_pk_fma_f32 v[158:159], v[150:151], v[110:111], v[158:159]
	v_pk_fma_f32 v[160:161], v[150:151], v[118:119], v[160:161]
	v_pk_fma_f32 v[162:163], v[150:151], v[126:127], v[162:163]
	v_pk_fma_f32 v[164:165], v[150:151], v[134:135], v[164:165]
	v_pk_fma_f32 v[156:157], v[152:153], v[104:105], v[156:157]
	v_pk_fma_f32 v[158:159], v[152:153], v[112:113], v[158:159]
	v_pk_fma_f32 v[160:161], v[152:153], v[120:121], v[160:161]
	v_pk_fma_f32 v[162:163], v[152:153], v[128:129], v[162:163]
	v_pk_fma_f32 v[164:165], v[152:153], v[136:137], v[164:165]
	v_pk_fma_f32 v[156:157], v[154:155], v[106:107], v[156:157]
	v_pk_fma_f32 v[158:159], v[154:155], v[114:115], v[158:159]
	v_pk_fma_f32 v[160:161], v[154:155], v[122:123], v[160:161]
	v_pk_fma_f32 v[162:163], v[154:155], v[130:131], v[162:163]
	v_pk_fma_f32 v[164:165], v[154:155], v[138:139], v[164:165]
	ds_read_b128 v[100:103], v26 offset:480
	ds_read_b128 v[104:107], v26 offset:496
	ds_read_b128 v[108:111], v26 offset:512
	ds_read_b128 v[112:115], v26 offset:528
	ds_read_b128 v[116:119], v26 offset:544
	ds_read_b128 v[120:123], v26 offset:560
	ds_read_b128 v[124:127], v26 offset:576
	ds_read_b128 v[128:131], v26 offset:592
	ds_read_b128 v[132:135], v26 offset:608
	ds_read_b128 v[136:139], v26 offset:624
	s_waitcnt vmcnt(7)
	v_lshlrev_b32_e32 v148, 16, v36
	v_and_b32_e32 v149, 0xffff0000, v36
	v_lshlrev_b32_e32 v150, 16, v37
	v_and_b32_e32 v151, 0xffff0000, v37
	v_lshlrev_b32_e32 v152, 16, v38
	v_and_b32_e32 v153, 0xffff0000, v38
	v_lshlrev_b32_e32 v154, 16, v39
	v_and_b32_e32 v155, 0xffff0000, v39
	global_load_dwordx4 v[36:39], v25, s[34:35] offset:160
	s_waitcnt lgkmcnt(10)
	v_pk_fma_f32 v[156:157], v[148:149], v[60:61], v[156:157]
	v_pk_fma_f32 v[158:159], v[148:149], v[68:69], v[158:159]
	v_pk_fma_f32 v[160:161], v[148:149], v[76:77], v[160:161]
	v_pk_fma_f32 v[162:163], v[148:149], v[84:85], v[162:163]
	v_pk_fma_f32 v[164:165], v[148:149], v[92:93], v[164:165]
	v_pk_fma_f32 v[156:157], v[150:151], v[62:63], v[156:157]
	v_pk_fma_f32 v[158:159], v[150:151], v[70:71], v[158:159]
	v_pk_fma_f32 v[160:161], v[150:151], v[78:79], v[160:161]
	v_pk_fma_f32 v[162:163], v[150:151], v[86:87], v[162:163]
	v_pk_fma_f32 v[164:165], v[150:151], v[94:95], v[164:165]
	v_pk_fma_f32 v[156:157], v[152:153], v[64:65], v[156:157]
	v_pk_fma_f32 v[158:159], v[152:153], v[72:73], v[158:159]
	v_pk_fma_f32 v[160:161], v[152:153], v[80:81], v[160:161]
	v_pk_fma_f32 v[162:163], v[152:153], v[88:89], v[162:163]
	v_pk_fma_f32 v[164:165], v[152:153], v[96:97], v[164:165]
	v_pk_fma_f32 v[156:157], v[154:155], v[66:67], v[156:157]
	v_pk_fma_f32 v[158:159], v[154:155], v[74:75], v[158:159]
	v_pk_fma_f32 v[160:161], v[154:155], v[82:83], v[160:161]
	v_pk_fma_f32 v[162:163], v[154:155], v[90:91], v[162:163]
	v_pk_fma_f32 v[164:165], v[154:155], v[98:99], v[164:165]
	ds_read_b128 v[60:63], v26 offset:640
	ds_read_b128 v[64:67], v26 offset:656
	ds_read_b128 v[68:71], v26 offset:672
	ds_read_b128 v[72:75], v26 offset:688
	ds_read_b128 v[76:79], v26 offset:704
	ds_read_b128 v[80:83], v26 offset:720
	ds_read_b128 v[84:87], v26 offset:736
	ds_read_b128 v[88:91], v26 offset:752
	ds_read_b128 v[92:95], v26 offset:768
	ds_read_b128 v[96:99], v26 offset:784
	s_waitcnt vmcnt(7)
	v_lshlrev_b32_e32 v148, 16, v40
	v_and_b32_e32 v149, 0xffff0000, v40
	v_lshlrev_b32_e32 v150, 16, v41
	v_and_b32_e32 v151, 0xffff0000, v41
	v_lshlrev_b32_e32 v152, 16, v42
	v_and_b32_e32 v153, 0xffff0000, v42
	v_lshlrev_b32_e32 v154, 16, v43
	v_and_b32_e32 v155, 0xffff0000, v43
	global_load_dwordx4 v[40:43], v25, s[34:35] offset:176
	s_waitcnt lgkmcnt(10)
	v_pk_fma_f32 v[156:157], v[148:149], v[100:101], v[156:157]
	v_pk_fma_f32 v[158:159], v[148:149], v[108:109], v[158:159]
	v_pk_fma_f32 v[160:161], v[148:149], v[116:117], v[160:161]
	v_pk_fma_f32 v[162:163], v[148:149], v[124:125], v[162:163]
	v_pk_fma_f32 v[164:165], v[148:149], v[132:133], v[164:165]
	v_pk_fma_f32 v[156:157], v[150:151], v[102:103], v[156:157]
	v_pk_fma_f32 v[158:159], v[150:151], v[110:111], v[158:159]
	v_pk_fma_f32 v[160:161], v[150:151], v[118:119], v[160:161]
	v_pk_fma_f32 v[162:163], v[150:151], v[126:127], v[162:163]
	v_pk_fma_f32 v[164:165], v[150:151], v[134:135], v[164:165]
	v_pk_fma_f32 v[156:157], v[152:153], v[104:105], v[156:157]
	v_pk_fma_f32 v[158:159], v[152:153], v[112:113], v[158:159]
	v_pk_fma_f32 v[160:161], v[152:153], v[120:121], v[160:161]
	v_pk_fma_f32 v[162:163], v[152:153], v[128:129], v[162:163]
	v_pk_fma_f32 v[164:165], v[152:153], v[136:137], v[164:165]
	v_pk_fma_f32 v[156:157], v[154:155], v[106:107], v[156:157]
	v_pk_fma_f32 v[158:159], v[154:155], v[114:115], v[158:159]
	v_pk_fma_f32 v[160:161], v[154:155], v[122:123], v[160:161]
	v_pk_fma_f32 v[162:163], v[154:155], v[130:131], v[162:163]
	v_pk_fma_f32 v[164:165], v[154:155], v[138:139], v[164:165]
	ds_read_b128 v[100:103], v26 offset:800
	ds_read_b128 v[104:107], v26 offset:816
	ds_read_b128 v[108:111], v26 offset:832
	ds_read_b128 v[112:115], v26 offset:848
	ds_read_b128 v[116:119], v26 offset:864
	ds_read_b128 v[120:123], v26 offset:880
	ds_read_b128 v[124:127], v26 offset:896
	ds_read_b128 v[128:131], v26 offset:912
	ds_read_b128 v[132:135], v26 offset:928
	ds_read_b128 v[136:139], v26 offset:944
	s_waitcnt vmcnt(7)
; __device__ __forceinline__ void cb_item(const bf16_t* WT, int ldw, int K, int n0, const float* shift, float* out, int ostride, int lane) {
;     ...
;     for (int k8 = 0; k8 < K; k8 += 8) {
;         const u32x4 q = *(const u32x4*)(wp + k8);
;         float w[8];
; #pragma unroll
;         for (int e = 0; e < 4; ++e) { w[2 * e] = __uint_as_float(q[e] << 16); w[2 * e + 1] = __uint_as_float(q[e] & 0xffff0000u); }
; #pragma unroll
;         for (int b = 0; b < 5; ++b) { const float* sp = shift + (size_t)b * 9216 + k8;
; #pragma unroll
;             for (int e = 0; e < 8; ++e) a[b] += w[e] * sp[e]; }
;     }
	v_lshlrev_b32_e32 v148, 16, v44
	v_and_b32_e32 v149, 0xffff0000, v44
	v_lshlrev_b32_e32 v150, 16, v45
	v_and_b32_e32 v151, 0xffff0000, v45
	v_lshlrev_b32_e32 v152, 16, v46
	v_and_b32_e32 v153, 0xffff0000, v46
	v_lshlrev_b32_e32 v154, 16, v47
	v_and_b32_e32 v155, 0xffff0000, v47
	global_load_dwordx4 v[44:47], v25, s[34:35] offset:192
	s_waitcnt lgkmcnt(10)
	v_pk_fma_f32 v[156:157], v[148:149], v[60:61], v[156:157]
	v_pk_fma_f32 v[158:159], v[148:149], v[68:69], v[158:159]
	v_pk_fma_f32 v[160:161], v[148:149], v[76:77], v[160:161]
	v_pk_fma_f32 v[162:163], v[148:149], v[84:85], v[162:163]
	v_pk_fma_f32 v[164:165], v[148:149], v[92:93], v[164:165]
	v_pk_fma_f32 v[156:157], v[150:151], v[62:63], v[156:157]
	v_pk_fma_f32 v[158:159], v[150:151], v[70:71], v[158:159]
	v_pk_fma_f32 v[160:161], v[150:151], v[78:79], v[160:161]
	v_pk_fma_f32 v[162:163], v[150:151], v[86:87], v[162:163]
	v_pk_fma_f32 v[164:165], v[150:151], v[94:95], v[164:165]
	v_pk_fma_f32 v[156:157], v[152:153], v[64:65], v[156:157]
	v_pk_fma_f32 v[158:159], v[152:153], v[72:73], v[158:159]
	v_pk_fma_f32 v[160:161], v[152:153], v[80:81], v[160:161]
	v_pk_fma_f32 v[162:163], v[152:153], v[88:89], v[162:163]
	v_pk_fma_f32 v[164:165], v[152:153], v[96:97], v[164:165]
	v_pk_fma_f32 v[156:157], v[154:155], v[66:67], v[156:157]
	v_pk_fma_f32 v[158:159], v[154:155], v[74:75], v[158:159]
	v_pk_fma_f32 v[160:161], v[154:155], v[82:83], v[160:161]
	v_pk_fma_f32 v[162:163], v[154:155], v[90:91], v[162:163]
	v_pk_fma_f32 v[164:165], v[154:155], v[98:99], v[164:165]
	ds_read_b128 v[60:63], v26 offset:960
	ds_read_b128 v[64:67], v26 offset:976
	ds_read_b128 v[68:71], v26 offset:992
	ds_read_b128 v[72:75], v26 offset:1008
	ds_read_b128 v[76:79], v26 offset:1024
	ds_read_b128 v[80:83], v26 offset:1040
	ds_read_b128 v[84:87], v26 offset:1056
	ds_read_b128 v[88:91], v26 offset:1072
	ds_read_b128 v[92:95], v26 offset:1088
	ds_read_b128 v[96:99], v26 offset:1104
	s_waitcnt vmcnt(7)
	v_lshlrev_b32_e32 v148, 16, v48
	v_and_b32_e32 v149, 0xffff0000, v48
	v_lshlrev_b32_e32 v150, 16, v49
	v_and_b32_e32 v151, 0xffff0000, v49
	v_lshlrev_b32_e32 v152, 16, v50
	v_and_b32_e32 v153, 0xffff0000, v50
	v_lshlrev_b32_e32 v154, 16, v51
	v_and_b32_e32 v155, 0xffff0000, v51
	global_load_dwordx4 v[48:51], v25, s[34:35] offset:208
	s_waitcnt lgkmcnt(10)
	v_pk_fma_f32 v[156:157], v[148:149], v[100:101], v[156:157]
	v_pk_fma_f32 v[158:159], v[148:149], v[108:109], v[158:159]
	v_pk_fma_f32 v[160:161], v[148:149], v[116:117], v[160:161]
	v_pk_fma_f32 v[162:163], v[148:149], v[124:125], v[162:163]
	v_pk_fma_f32 v[164:165], v[148:149], v[132:133], v[164:165]
	v_pk_fma_f32 v[156:157], v[150:151], v[102:103], v[156:157]
	v_pk_fma_f32 v[158:159], v[150:151], v[110:111], v[158:159]
	v_pk_fma_f32 v[160:161], v[150:151], v[118:119], v[160:161]
	v_pk_fma_f32 v[162:163], v[150:151], v[126:127], v[162:163]
	v_pk_fma_f32 v[164:165], v[150:151], v[134:135], v[164:165]
	v_pk_fma_f32 v[156:157], v[152:153], v[104:105], v[156:157]
	v_pk_fma_f32 v[158:159], v[152:153], v[112:113], v[158:159]
	v_pk_fma_f32 v[160:161], v[152:153], v[120:121], v[160:161]
	v_pk_fma_f32 v[162:163], v[152:153], v[128:129], v[162:163]
	v_pk_fma_f32 v[164:165], v[152:153], v[136:137], v[164:165]
	v_pk_fma_f32 v[156:157], v[154:155], v[106:107], v[156:157]
	v_pk_fma_f32 v[158:159], v[154:155], v[114:115], v[158:159]
	v_pk_fma_f32 v[160:161], v[154:155], v[122:123], v[160:161]
	v_pk_fma_f32 v[162:163], v[154:155], v[130:131], v[162:163]
	v_pk_fma_f32 v[164:165], v[154:155], v[138:139], v[164:165]
	ds_read_b128 v[100:103], v26 offset:1120
	ds_read_b128 v[104:107], v26 offset:1136
	ds_read_b128 v[108:111], v26 offset:1152
	ds_read_b128 v[112:115], v26 offset:1168
	ds_read_b128 v[116:119], v26 offset:1184
	ds_read_b128 v[120:123], v26 offset:1200
	ds_read_b128 v[124:127], v26 offset:1216
	ds_read_b128 v[128:131], v26 offset:1232
	ds_read_b128 v[132:135], v26 offset:1248
	ds_read_b128 v[136:139], v26 offset:1264
	s_waitcnt vmcnt(7)
; __device__ __forceinline__ void cb_item(const bf16_t* WT, int ldw, int K, int n0, const float* shift, float* out, int ostride, int lane) {
;     ...
;     for (int k8 = 0; k8 < K; k8 += 8) {
;         const u32x4 q = *(const u32x4*)(wp + k8);
;         float w[8];
; #pragma unroll
;         for (int e = 0; e < 4; ++e) { w[2 * e] = __uint_as_float(q[e] << 16); w[2 * e + 1] = __uint_as_float(q[e] & 0xffff0000u); }
; #pragma unroll
;         for (int b = 0; b < 5; ++b) { const float* sp = shift + (size_t)b * 9216 + k8;
; #pragma unroll
;             for (int e = 0; e < 8; ++e) a[b] += w[e] * sp[e]; }
;     }
; #pragma unroll
;     for (int b = 0; b < 5; ++b) out[(size_t)b * ostride + n0 + lane] = a[b];
	v_lshlrev_b32_e32 v148, 16, v52
	v_and_b32_e32 v149, 0xffff0000, v52
	v_lshlrev_b32_e32 v150, 16, v53
	v_and_b32_e32 v151, 0xffff0000, v53
	v_lshlrev_b32_e32 v152, 16, v54
	v_and_b32_e32 v153, 0xffff0000, v54
	v_lshlrev_b32_e32 v154, 16, v55
	v_and_b32_e32 v155, 0xffff0000, v55
	global_load_dwordx4 v[52:55], v25, s[34:35] offset:224
	s_waitcnt lgkmcnt(10)
	v_pk_fma_f32 v[156:157], v[148:149], v[60:61], v[156:157]
	v_pk_fma_f32 v[158:159], v[148:149], v[68:69], v[158:159]
	v_pk_fma_f32 v[160:161], v[148:149], v[76:77], v[160:161]
	v_pk_fma_f32 v[162:163], v[148:149], v[84:85], v[162:163]
	v_pk_fma_f32 v[164:165], v[148:149], v[92:93], v[164:165]
	v_pk_fma_f32 v[156:157], v[150:151], v[62:63], v[156:157]
	v_pk_fma_f32 v[158:159], v[150:151], v[70:71], v[158:159]
	v_pk_fma_f32 v[160:161], v[150:151], v[78:79], v[160:161]
	v_pk_fma_f32 v[162:163], v[150:151], v[86:87], v[162:163]
	v_pk_fma_f32 v[164:165], v[150:151], v[94:95], v[164:165]
	v_pk_fma_f32 v[156:157], v[152:153], v[64:65], v[156:157]
	v_pk_fma_f32 v[158:159], v[152:153], v[72:73], v[158:159]
	v_pk_fma_f32 v[160:161], v[152:153], v[80:81], v[160:161]
	v_pk_fma_f32 v[162:163], v[152:153], v[88:89], v[162:163]
	v_pk_fma_f32 v[164:165], v[152:153], v[96:97], v[164:165]
	v_pk_fma_f32 v[156:157], v[154:155], v[66:67], v[156:157]
	v_pk_fma_f32 v[158:159], v[154:155], v[74:75], v[158:159]
	v_pk_fma_f32 v[160:161], v[154:155], v[82:83], v[160:161]
	v_pk_fma_f32 v[162:163], v[154:155], v[90:91], v[162:163]
	v_pk_fma_f32 v[164:165], v[154:155], v[98:99], v[164:165]
	ds_read_b128 v[60:63], v26 offset:1280
	ds_read_b128 v[64:67], v26 offset:1296
	ds_read_b128 v[68:71], v26 offset:1312
	ds_read_b128 v[72:75], v26 offset:1328
	ds_read_b128 v[76:79], v26 offset:1344
	ds_read_b128 v[80:83], v26 offset:1360
	ds_read_b128 v[84:87], v26 offset:1376
	ds_read_b128 v[88:91], v26 offset:1392
	ds_read_b128 v[92:95], v26 offset:1408
	ds_read_b128 v[96:99], v26 offset:1424
	s_waitcnt vmcnt(7)
	v_lshlrev_b32_e32 v148, 16, v56
	v_and_b32_e32 v149, 0xffff0000, v56
	v_lshlrev_b32_e32 v150, 16, v57
	v_and_b32_e32 v151, 0xffff0000, v57
	v_lshlrev_b32_e32 v152, 16, v58
	v_and_b32_e32 v153, 0xffff0000, v58
	v_lshlrev_b32_e32 v154, 16, v59
	v_and_b32_e32 v155, 0xffff0000, v59
	global_load_dwordx4 v[56:59], v25, s[34:35] offset:240
	s_waitcnt lgkmcnt(10)
	v_pk_fma_f32 v[156:157], v[148:149], v[100:101], v[156:157]
	v_pk_fma_f32 v[158:159], v[148:149], v[108:109], v[158:159]
	v_pk_fma_f32 v[160:161], v[148:149], v[116:117], v[160:161]
	v_pk_fma_f32 v[162:163], v[148:149], v[124:125], v[162:163]
	v_pk_fma_f32 v[164:165], v[148:149], v[132:133], v[164:165]
	v_pk_fma_f32 v[156:157], v[150:151], v[102:103], v[156:157]
	v_pk_fma_f32 v[158:159], v[150:151], v[110:111], v[158:159]
	v_pk_fma_f32 v[160:161], v[150:151], v[118:119], v[160:161]
	v_pk_fma_f32 v[162:163], v[150:151], v[126:127], v[162:163]
	v_pk_fma_f32 v[164:165], v[150:151], v[134:135], v[164:165]
	v_pk_fma_f32 v[156:157], v[152:153], v[104:105], v[156:157]
	v_pk_fma_f32 v[158:159], v[152:153], v[112:113], v[158:159]
	v_pk_fma_f32 v[160:161], v[152:153], v[120:121], v[160:161]
	v_pk_fma_f32 v[162:163], v[152:153], v[128:129], v[162:163]
	v_pk_fma_f32 v[164:165], v[152:153], v[136:137], v[164:165]
	v_pk_fma_f32 v[156:157], v[154:155], v[106:107], v[156:157]
	v_pk_fma_f32 v[158:159], v[154:155], v[114:115], v[158:159]
	v_pk_fma_f32 v[160:161], v[154:155], v[122:123], v[160:161]
	v_pk_fma_f32 v[162:163], v[154:155], v[130:131], v[162:163]
	v_pk_fma_f32 v[164:165], v[154:155], v[138:139], v[164:165]
	v_add_u32_e32 v25, 0x80, v25
	v_add_u32_e32 v26, 0x500, v26
	s_add_i32 s41, s41, -1
	s_cmp_lg_u32 s41, 0
	s_cbranch_scc1 .Lcb1_loop_d_0
	s_waitcnt vmcnt(0) lgkmcnt(0)
	s_mov_b64 s[0:1], s[38:39]
	v_lshlrev_b32_e32 v27, 2, v16
	v_add_f32_e32 v20, v156, v157
	v_add_f32_e32 v21, v158, v159
	v_add_f32_e32 v22, v160, v161
	v_add_f32_e32 v23, v162, v163
	v_add_f32_e32 v24, v164, v165
	global_store_dword v27, v20, s[0:1]
	s_add_u32 s0, s0, s40
	s_addc_u32 s1, s1, 0
	global_store_dword v27, v21, s[0:1]
	s_add_u32 s0, s0, s40
	s_addc_u32 s1, s1, 0
	global_store_dword v27, v22, s[0:1]
	s_add_u32 s0, s0, s40
	s_addc_u32 s1, s1, 0
	global_store_dword v27, v23, s[0:1]
	s_add_u32 s0, s0, s40
	s_addc_u32 s1, s1, 0
	global_store_dword v27, v24, s[0:1]

; __device__ __forceinline__ float wave_sum(float v) {
; #pragma unroll
;     for (int o = 1; o < 64; o <<= 1) v += __shfl_xor(v, o);
;     return v;
; __device__ __forceinline__ void prenorm_rows(const float* src0, const float* src1, int row_lo, int row_hi, const float* g, const float* scale, float* SS, bf16_t* HB) {
;     const int lane = threadIdx.x & 63, wave = threadIdx.x >> 6, gw = blockIdx.x * 8 + wave, NGW = gridDim.x * 8;
;     for (int row = row_lo + gw; row < row_hi; row += 2 * NGW) {
;         const int rowb = row + NGW; const bool hasb = rowb < row_hi; const int rb = hasb ? rowb : row;
;         const float* srca = row < NTOK ? src0 + (size_t)row * D : src1 + (size_t)(row - NTOK) * D;
;         const float* srcb = rb < NTOK ? src0 + (size_t)rb * D : src1 + (size_t)(rb - NTOK) * D;
;         const int mba = row < NTOK ? (row >> 12) : 4, mbb = rb < NTOK ? (rb >> 12) : 4;
;         const f32x4* xa = (const f32x4*)srca + lane; const f32x4* xb = (const f32x4*)srcb + lane;
.Lph2_cbdone:
	v_mbcnt_hi_u32_b32 v0, -1, v220
	v_and_b32_e32 v1, 64, v0
	v_add_u32_e32 v1, 64, v1
	v_xor_b32_e32 v2, 1, v0
	v_cmp_lt_i32_e32 vcc, v2, v1
	v_mov_b32_e32 v193, 0
	s_mov_b64 s[0:1], 0x1000
	v_cndmask_b32_e32 v2, v0, v2, vcc
	v_lshlrev_b32_e32 v56, 2, v2
	v_xor_b32_e32 v2, 2, v0
	v_cmp_lt_i32_e32 vcc, v2, v1
	v_mov_b32_e32 v195, v193
	v_lshl_add_u64 v[40:41], s[28:29], 0, v[192:193]
	v_cndmask_b32_e32 v2, v0, v2, vcc
	v_lshlrev_b32_e32 v57, 2, v2
	v_xor_b32_e32 v2, 4, v0
	v_cmp_lt_i32_e32 vcc, v2, v1
	v_lshl_add_u64 v[44:45], s[72:73], 0, v[194:195]
	s_ashr_i32 s95, s94, 31
	v_cndmask_b32_e32 v2, v0, v2, vcc
	v_lshlrev_b32_e32 v58, 2, v2
	v_xor_b32_e32 v2, 8, v0
	v_cmp_lt_i32_e32 vcc, v2, v1
	s_mov_b64 s[24:25], 0
	s_movk_i32 s26, 0x4000
	v_cndmask_b32_e32 v2, v0, v2, vcc
	v_lshlrev_b32_e32 v59, 2, v2
	v_xor_b32_e32 v2, 16, v0
	v_cmp_lt_i32_e32 vcc, v2, v1
	v_mov_b32_e32 v62, s21
	v_mov_b32_e32 v63, s17
	v_cndmask_b32_e32 v2, v0, v2, vcc
	v_lshlrev_b32_e32 v60, 2, v2
	v_xor_b32_e32 v2, 32, v0
	v_cmp_lt_i32_e32 vcc, v2, v1
	v_mov_b32_e32 v64, s20
	v_mov_b32_e32 v65, s16
	v_cndmask_b32_e32 v0, v0, v2, vcc
	v_lshlrev_b32_e32 v61, 2, v0
	v_lshl_add_u64 v[0:1], s[80:81], 0, v[192:193]
	v_cmp_eq_u32_e32 vcc, 0, v178
	v_lshl_add_u64 v[42:43], v[0:1], 0, s[0:1]
	v_lshlrev_b32_e32 v46, 4, v178
	v_mov_b32_e32 v47, v193
	s_movk_i32 s20, 0x43ff
	s_cmpk_lg_u32 s82, 0x100
	s_cbranch_scc1 .Lq_static_a
	s_mov_b64 s[100:101], exec
	s_mov_b64 exec, 1
	v_mov_b32_e32 v254, 0x23f10
	v_mov_b32_e32 v255, 1
	ds_add_rtn_u32 v255, v254, v255
	s_waitcnt lgkmcnt(0)
	v_readfirstlane_b32 s98, v255
	s_mov_b64 exec, s[100:101]
	s_and_b32 s99, s98, 7
	s_lshr_b32 s98, s98, 3
	s_lshl_b32 s98, s98, 12
	s_add_i32 s98, s98, s99
	s_lshl_b32 s99, s84, 3
	s_add_i32 s98, s98, s99
	v_mov_b32_e32 v48, s98
	s_branch .Lq_done_a
.Lq_static_a:
	v_mov_b32_e32 v48, v181

; __device__ __forceinline__ void prenorm_rows(const float* src0, const float* src1, int row_lo, int row_hi, const float* g, const float* scale, float* SS, bf16_t* HB) {
;     ...
;     for (int row = row_lo + gw; row < row_hi; row += 2 * NGW) {
.LBB0_136:
	s_or_b64 exec, exec, s[12:13]
	s_cmpk_lg_u32 s82, 0x100
	s_cbranch_scc1 .Lq_static_b
	s_mov_b64 s[100:101], exec
	s_mov_b64 exec, 1
	v_mov_b32_e32 v254, 0x23f10
	v_mov_b32_e32 v255, 1
	ds_add_rtn_u32 v255, v254, v255
	s_waitcnt lgkmcnt(0)
	v_readfirstlane_b32 s98, v255
	s_mov_b64 exec, s[100:101]
	s_and_b32 s99, s98, 7
	s_lshr_b32 s98, s98, 3
	s_lshl_b32 s98, s98, 12
	s_add_i32 s98, s98, s99
	s_lshl_b32 s99, s84, 3
	s_add_i32 s98, s98, s99
	v_mov_b32_e32 v48, s98
	s_branch .Lq_done_b
.Lq_static_b:
	v_add_u32_e32 v48, s94, v66
.Lq_done_b:
	v_cmp_lt_i32_e64 s[0:1], s20, v48
	s_or_b64 s[24:25], s[0:1], s[24:25]
	s_andn2_b64 exec, exec, s[24:25]
	s_cbranch_execz .LBB0_148

; __device__ __forceinline__ void cb_tables(const Params& p) {
;     ...
;     for (int it = blockIdx.x + G * wave; it < 4 * 88 + 40 + 32; it += 8 * G) {
;         if (it < 352) { const int mi = it / 88, ch = it % 88, layer = mi >> 1, sub = mi & 1;
.LBB0_151:
	s_cmpk_lg_u32 s82, 0x100
	s_cbranch_scc1 .Lcb_noskip
	s_mov_b64 s[46:47], exec
	s_branch .LBB0_150
